# P7/P10 residual epilogues: xb loads of all row blocks hoisted above the first block (no per-block vmcnt(0) behind stores/atomics)
# speedup vs baseline: 1.0035x; 1.0035x over previous
; __device__ __forceinline__ unsigned cvtpk(float lo, float hi) { f32x2_t v = {lo, hi}; bf16x2_t b = __builtin_convertvector(v, bf16x2_t); return __builtin_bit_cast(unsigned, b); }
; __device__ __forceinline__ float bflo(unsigned w) { return __uint_as_float(w << 16); }
; __device__ __forceinline__ float bfhi(unsigned w) { return __uint_as_float(w & 0xffff0000u); }
;     __device__ __forceinline__ void operator()(const f32x4 (&acc)[2][2][4][2], const Unit& u, int wr, int wc, int fr, int fq) const {
;         const int row0 = u.pm * 256 + wr * 64 + fr, col0 = (u.pn & 7) * 256 + wc * 32 + 8 * fq;
; #pragma unroll
;         for (int ai = 0; ai < 2; ++ai)
; #pragma unroll
;             for (int m = 0; m < 4; ++m) {
;                 const int row = row0 + ai * 128 + m * 16; float s = 0.f;
; #pragma unroll
;                 for (int bj = 0; bj < 2; ++bj) {
;                     const size_t off = (size_t)row * D + col0 + bj * 128;
;                     f32x4 b0, b1;
;                     if (BASE_F32) { b0 = __builtin_nontemporal_load((const f32x4*)(base + off)); b1 = __builtin_nontemporal_load((const f32x4*)(base + off + 4)); }
;                     else { const u32x4 w = *(const u32x4*)(xb + off); b0 = (f32x4){bflo(w.x), bfhi(w.x), bflo(w.y), bfhi(w.y)}; b1 = (f32x4){bflo(w.z), bfhi(w.z), bflo(w.w), bfhi(w.w)}; }
;                     const f32x4 h0 = b0 + acc[ai][bj][m][0] * scale, h1 = b1 + acc[ai][bj][m][1] * scale;
;                     if (OUT_F32) { *(f32x4*)(out + off) = h0; *(f32x4*)(out + off + 4) = h1; }
;                     else { u32x4 w; w.x = cvtpk(h0[0], h0[1]); w.y = cvtpk(h0[2], h0[3]); w.z = cvtpk(h1[0], h1[1]); w.w = cvtpk(h1[2], h1[3]); st16(xb + off, w); }
;                     s += (h0[0] * h0[0] + h0[1] * h0[1]) + (h0[2] * h0[2] + h0[3] * h0[3]) + (h1[0] * h1[0] + h1[1] * h1[1]) + (h1[2] * h1[2] + h1[3] * h1[3]);
;                 }
;                 s += __shfl_xor(s, 16); s += __shfl_xor(s, 32);
;                 if (fq == 0) __hip_atomic_fetch_add(ssq_out + row, s, __ATOMIC_RELAXED, __HIP_MEMORY_SCOPE_AGENT);
;             }
.LBB0_1333:
	v_lshl_add_u32 v148, s24, 8, v152
	s_lshl_b32 s17, s26, 8
	s_and_b32 s17, s17, 0x700
	v_ashrrev_i32_e32 v149, 31, v148
	v_or_b32_e32 v138, s17, v154
	v_lshlrev_b64 v[160:161], 12, v[148:149]
	v_lshl_add_u64 v[160:161], s[36:37], 0, v[160:161]
	v_lshlrev_b32_e32 v138, 1, v138
	v_lshl_add_u64 v[170:171], v[160:161], 0, v[138:139]
	global_load_dwordx4 v[162:165], v[170:171], off
	global_load_dwordx4 v[166:169], v[170:171], off offset:256
	v_or_b32_e32 v182, 16, v148
	v_ashrrev_i32_e32 v183, 31, v182
	v_lshlrev_b64 v[182:183], 12, v[182:183]
	v_lshl_add_u64 v[182:183], s[36:37], 0, v[182:183]
	v_lshl_add_u64 v[182:183], v[182:183], 0, v[138:139]
	global_load_dwordx4 v[184:187], v[182:183], off
	global_load_dwordx4 v[192:195], v[182:183], off offset:256
	v_or_b32_e32 v182, 32, v148
	v_ashrrev_i32_e32 v183, 31, v182
	v_lshlrev_b64 v[182:183], 12, v[182:183]
	v_lshl_add_u64 v[182:183], s[36:37], 0, v[182:183]
	v_lshl_add_u64 v[182:183], v[182:183], 0, v[138:139]
	global_load_dwordx4 v[196:199], v[182:183], off
	global_load_dwordx4 v[200:203], v[182:183], off offset:256
	v_or_b32_e32 v182, 48, v148
	v_ashrrev_i32_e32 v183, 31, v182
	v_lshlrev_b64 v[182:183], 12, v[182:183]
	v_lshl_add_u64 v[182:183], s[36:37], 0, v[182:183]
	v_lshl_add_u64 v[182:183], v[182:183], 0, v[138:139]
	global_load_dwordx4 v[204:207], v[182:183], off
	global_load_dwordx4 v[208:211], v[182:183], off offset:256
	v_add_u32_e32 v182, 0x80, v148
	v_ashrrev_i32_e32 v183, 31, v182
	v_lshlrev_b64 v[182:183], 12, v[182:183]
	v_lshl_add_u64 v[182:183], s[36:37], 0, v[182:183]
	v_lshl_add_u64 v[182:183], v[182:183], 0, v[138:139]
	global_load_dwordx4 v[212:215], v[182:183], off
	global_load_dwordx4 v[216:219], v[182:183], off offset:256
	v_add_u32_e32 v182, 0x90, v148
	v_ashrrev_i32_e32 v183, 31, v182
	v_lshlrev_b64 v[182:183], 12, v[182:183]
	v_lshl_add_u64 v[182:183], s[36:37], 0, v[182:183]
	v_lshl_add_u64 v[182:183], v[182:183], 0, v[138:139]
	global_load_dwordx4 v[220:223], v[182:183], off
	global_load_dwordx4 v[224:227], v[182:183], off offset:256
	v_add_u32_e32 v182, 0xa0, v148
	v_ashrrev_i32_e32 v183, 31, v182
	v_lshlrev_b64 v[182:183], 12, v[182:183]
	v_lshl_add_u64 v[182:183], s[36:37], 0, v[182:183]
	v_lshl_add_u64 v[182:183], v[182:183], 0, v[138:139]
	global_load_dwordx4 v[228:231], v[182:183], off
	global_load_dwordx4 v[232:235], v[182:183], off offset:256
	v_and_b32_e32 v160, 64, v158
	v_xor_b32_e32 v159, 16, v158
	v_add_u32_e32 v160, 64, v160
	v_xor_b32_e32 v161, 32, v158
	v_cmp_lt_i32_e32 vcc, v159, v160
	s_waitcnt vmcnt(12)
	v_lshlrev_b32_e32 v172, 16, v162
	v_cndmask_b32_e32 v159, v158, v159, vcc
	v_cmp_lt_i32_e32 vcc, v161, v160
	v_and_b32_e32 v173, 0xffff0000, v162
	v_lshlrev_b32_e32 v162, 16, v163
	v_and_b32_e32 v163, 0xffff0000, v163
	v_lshlrev_b32_e32 v176, 16, v166
	v_and_b32_e32 v177, 0xffff0000, v166
	v_lshlrev_b32_e32 v166, 16, v167
	v_and_b32_e32 v167, 0xffff0000, v167
	v_cndmask_b32_e32 v161, v158, v161, vcc
	v_lshlrev_b32_e32 v174, 16, v164
	v_and_b32_e32 v175, 0xffff0000, v164
	v_lshlrev_b32_e32 v164, 16, v165
	v_and_b32_e32 v165, 0xffff0000, v165
	v_lshlrev_b32_e32 v180, 16, v168
	v_and_b32_e32 v181, 0xffff0000, v168
	v_lshlrev_b32_e32 v168, 16, v169
	v_and_b32_e32 v169, 0xffff0000, v169
	v_pk_add_f32 v[128:129], v[128:129], v[162:163]
	v_pk_add_f32 v[126:127], v[126:127], v[172:173]
	v_pk_add_f32 v[120:121], v[120:121], v[166:167]
	v_pk_add_f32 v[118:119], v[118:119], v[176:177]
	v_lshlrev_b32_e32 v160, 2, v159
	v_lshlrev_b32_e32 v159, 2, v161
	v_pk_add_f32 v[124:125], v[124:125], v[164:165]
	v_pk_add_f32 v[122:123], v[122:123], v[174:175]
	v_pk_add_f32 v[162:163], v[116:117], v[168:169]
	v_pk_add_f32 v[164:165], v[114:115], v[180:181]
	v_mul_f32_e32 v116, v127, v127
	v_mul_f32_e32 v117, v129, v129
	v_mul_f32_e32 v161, v119, v119
	v_mul_f32_e32 v166, v121, v121
	v_cvt_pk_bf16_f32 v114, v126, v127
	v_mul_f32_e32 v127, v123, v123
	v_mul_f32_e32 v167, v165, v165
	v_fmac_f32_e32 v116, v126, v126
	v_fmac_f32_e32 v117, v128, v128
	v_fmac_f32_e32 v161, v118, v118
	v_fmac_f32_e32 v166, v120, v120
	v_cvt_pk_bf16_f32 v115, v128, v129
	v_mul_f32_e32 v129, v125, v125
	v_mul_f32_e32 v168, v163, v163
	v_fmac_f32_e32 v127, v122, v122
	v_fmac_f32_e32 v167, v164, v164
	v_add_f32_e32 v116, v116, v117
	v_add_f32_e32 v117, v161, v166
	v_fmac_f32_e32 v129, v124, v124
	v_fmac_f32_e32 v168, v162, v162
	v_add_f32_e32 v116, v127, v116
	v_add_f32_e32 v117, v167, v117
	v_add_f32_e32 v116, v129, v116
	v_add_f32_e32 v117, v168, v117
	v_add_f32_e32 v126, v116, v117
	ds_bpermute_b32 v127, v160, v126
	v_cvt_pk_bf16_f32 v116, v122, v123
	v_cvt_pk_bf16_f32 v117, v124, v125
	global_store_dwordx4 v[170:171], v[114:117], off
	s_waitcnt lgkmcnt(0)
	s_nop 0
	v_add_f32_e32 v114, v126, v127
	ds_bpermute_b32 v115, v159, v114
	v_cvt_pk_bf16_f32 v116, v118, v119
	v_cvt_pk_bf16_f32 v117, v120, v121
	v_cvt_pk_bf16_f32 v118, v164, v165
	v_cvt_pk_bf16_f32 v119, v162, v163
	global_store_dwordx4 v[170:171], v[116:119], off offset:256
	s_and_saveexec_b64 s[24:25], s[2:3]
	s_cbranch_execz .LBB0_1335
	v_lshl_add_u64 v[116:117], v[148:149], 2, s[6:7]
	s_waitcnt lgkmcnt(0)
	v_add_f32_e32 v114, v114, v115
	global_atomic_add_f32 v[116:117], v114, off
; __device__ __forceinline__ unsigned cvtpk(float lo, float hi) { f32x2_t v = {lo, hi}; bf16x2_t b = __builtin_convertvector(v, bf16x2_t); return __builtin_bit_cast(unsigned, b); }
; __device__ __forceinline__ float bflo(unsigned w) { return __uint_as_float(w << 16); }
; __device__ __forceinline__ float bfhi(unsigned w) { return __uint_as_float(w & 0xffff0000u); }
;     __device__ __forceinline__ void operator()(const f32x4 (&acc)[2][2][4][2], const Unit& u, int wr, int wc, int fr, int fq) const {
;         const int row0 = u.pm * 256 + wr * 64 + fr, col0 = (u.pn & 7) * 256 + wc * 32 + 8 * fq;
; #pragma unroll
;         for (int ai = 0; ai < 2; ++ai)
; #pragma unroll
;             for (int m = 0; m < 4; ++m) {
;                 const int row = row0 + ai * 128 + m * 16; float s = 0.f;
; #pragma unroll
;                 for (int bj = 0; bj < 2; ++bj) {
;                     const size_t off = (size_t)row * D + col0 + bj * 128;
;                     f32x4 b0, b1;
;                     if (BASE_F32) { b0 = __builtin_nontemporal_load((const f32x4*)(base + off)); b1 = __builtin_nontemporal_load((const f32x4*)(base + off + 4)); }
;                     else { const u32x4 w = *(const u32x4*)(xb + off); b0 = (f32x4){bflo(w.x), bfhi(w.x), bflo(w.y), bfhi(w.y)}; b1 = (f32x4){bflo(w.z), bfhi(w.z), bflo(w.w), bfhi(w.w)}; }
;                     const f32x4 h0 = b0 + acc[ai][bj][m][0] * scale, h1 = b1 + acc[ai][bj][m][1] * scale;
;                     if (OUT_F32) { *(f32x4*)(out + off) = h0; *(f32x4*)(out + off + 4) = h1; }
;                     else { u32x4 w; w.x = cvtpk(h0[0], h0[1]); w.y = cvtpk(h0[2], h0[3]); w.z = cvtpk(h1[0], h1[1]); w.w = cvtpk(h1[2], h1[3]); st16(xb + off, w); }
;                     s += (h0[0] * h0[0] + h0[1] * h0[1]) + (h0[2] * h0[2] + h0[3] * h0[3]) + (h1[0] * h1[0] + h1[1] * h1[1]) + (h1[2] * h1[2] + h1[3] * h1[3]);
;                 }
;                 s += __shfl_xor(s, 16); s += __shfl_xor(s, 32);
;                 if (fq == 0) __hip_atomic_fetch_add(ssq_out + row, s, __ATOMIC_RELAXED, __HIP_MEMORY_SCOPE_AGENT);
;             }
.LBB0_1335:
	s_or_b64 exec, exec, s[24:25]
	v_or_b32_e32 v114, 16, v148
	s_waitcnt lgkmcnt(0)
	v_ashrrev_i32_e32 v115, 31, v114
	v_lshlrev_b64 v[116:117], 12, v[114:115]
	v_lshl_add_u64 v[116:117], s[36:37], 0, v[116:117]
	v_lshl_add_u64 v[124:125], v[116:117], 0, v[138:139]
	s_waitcnt vmcnt(13)
	v_lshlrev_b32_e32 v126, 16, v184
	v_and_b32_e32 v127, 0xffff0000, v184
	v_lshlrev_b32_e32 v116, 16, v185
	v_and_b32_e32 v117, 0xffff0000, v185
	s_waitcnt vmcnt(12)
	v_lshlrev_b32_e32 v162, 16, v192
	v_and_b32_e32 v163, 0xffff0000, v192
	v_lshlrev_b32_e32 v120, 16, v193
	v_and_b32_e32 v121, 0xffff0000, v193
	v_lshlrev_b32_e32 v128, 16, v186
	v_and_b32_e32 v129, 0xffff0000, v186
	v_lshlrev_b32_e32 v118, 16, v187
	v_and_b32_e32 v119, 0xffff0000, v187
	v_lshlrev_b32_e32 v164, 16, v194
	v_and_b32_e32 v165, 0xffff0000, v194
	v_lshlrev_b32_e32 v122, 16, v195
	v_and_b32_e32 v123, 0xffff0000, v195
	v_add_u32_e32 v182, 0xb0, v148
	v_ashrrev_i32_e32 v183, 31, v182
	v_lshlrev_b64 v[182:183], 12, v[182:183]
	v_lshl_add_u64 v[182:183], s[36:37], 0, v[182:183]
	v_lshl_add_u64 v[182:183], v[182:183], 0, v[138:139]
	global_load_dwordx4 v[184:187], v[182:183], off
	global_load_dwordx4 v[192:195], v[182:183], off offset:256
	v_pk_add_f32 v[112:113], v[112:113], v[116:117]
	v_pk_add_f32 v[110:111], v[110:111], v[126:127]
	v_pk_add_f32 v[104:105], v[104:105], v[120:121]
	v_pk_add_f32 v[102:103], v[102:103], v[162:163]
	v_pk_add_f32 v[108:109], v[108:109], v[118:119]
	v_pk_add_f32 v[106:107], v[106:107], v[128:129]
	v_pk_add_f32 v[116:117], v[100:101], v[122:123]
	v_pk_add_f32 v[118:119], v[98:99], v[164:165]
	v_mul_f32_e32 v100, v111, v111
	v_mul_f32_e32 v101, v113, v113
	v_mul_f32_e32 v120, v103, v103
	v_mul_f32_e32 v121, v105, v105
	v_cvt_pk_bf16_f32 v98, v110, v111
	v_mul_f32_e32 v111, v107, v107
	v_mul_f32_e32 v122, v119, v119
	v_fmac_f32_e32 v100, v110, v110
	v_fmac_f32_e32 v101, v112, v112
	v_fmac_f32_e32 v120, v102, v102
	v_fmac_f32_e32 v121, v104, v104
	v_cvt_pk_bf16_f32 v99, v112, v113
	v_mul_f32_e32 v113, v109, v109
	v_mul_f32_e32 v123, v117, v117
	v_fmac_f32_e32 v111, v106, v106
	v_fmac_f32_e32 v122, v118, v118
	v_add_f32_e32 v100, v100, v101
	v_add_f32_e32 v101, v120, v121
	v_fmac_f32_e32 v113, v108, v108
	v_fmac_f32_e32 v123, v116, v116
	v_add_f32_e32 v100, v111, v100
	v_add_f32_e32 v101, v122, v101
	v_add_f32_e32 v100, v113, v100
	v_add_f32_e32 v101, v123, v101
	v_add_f32_e32 v110, v100, v101
	ds_bpermute_b32 v111, v160, v110
	v_cvt_pk_bf16_f32 v100, v106, v107
	v_cvt_pk_bf16_f32 v101, v108, v109
	global_store_dwordx4 v[124:125], v[98:101], off
	s_waitcnt lgkmcnt(0)
	s_nop 0
	v_add_f32_e32 v98, v110, v111
	ds_bpermute_b32 v99, v159, v98
	v_cvt_pk_bf16_f32 v100, v102, v103
	v_cvt_pk_bf16_f32 v101, v104, v105
	v_cvt_pk_bf16_f32 v102, v118, v119
	v_cvt_pk_bf16_f32 v103, v116, v117
	global_store_dwordx4 v[124:125], v[100:103], off offset:256
	s_and_saveexec_b64 s[24:25], s[2:3]
	s_cbranch_execz .LBB0_1337
	v_lshl_add_u64 v[100:101], v[114:115], 2, s[6:7]
	s_waitcnt lgkmcnt(0)
	v_add_f32_e32 v98, v98, v99
	global_atomic_add_f32 v[100:101], v98, off
.LBB0_1337:
	s_or_b64 exec, exec, s[24:25]
	v_or_b32_e32 v98, 32, v148
	s_waitcnt lgkmcnt(0)
	v_ashrrev_i32_e32 v99, 31, v98
	v_lshlrev_b64 v[100:101], 12, v[98:99]
	v_lshl_add_u64 v[100:101], s[36:37], 0, v[100:101]
	v_lshl_add_u64 v[108:109], v[100:101], 0, v[138:139]
	s_waitcnt vmcnt(15)
	v_lshlrev_b32_e32 v110, 16, v196
	v_and_b32_e32 v111, 0xffff0000, v196
	v_lshlrev_b32_e32 v100, 16, v197
	v_and_b32_e32 v101, 0xffff0000, v197
	s_waitcnt vmcnt(14)
	v_lshlrev_b32_e32 v114, 16, v200
	v_and_b32_e32 v115, 0xffff0000, v200
	v_lshlrev_b32_e32 v104, 16, v201
	v_and_b32_e32 v105, 0xffff0000, v201
	v_lshlrev_b32_e32 v112, 16, v198
	v_and_b32_e32 v113, 0xffff0000, v198
	v_lshlrev_b32_e32 v102, 16, v199
	v_and_b32_e32 v103, 0xffff0000, v199
	v_lshlrev_b32_e32 v116, 16, v202
	v_and_b32_e32 v117, 0xffff0000, v202
	v_lshlrev_b32_e32 v106, 16, v203
	v_and_b32_e32 v107, 0xffff0000, v203
	v_pk_add_f32 v[96:97], v[96:97], v[100:101]
	v_pk_add_f32 v[94:95], v[94:95], v[110:111]
	v_pk_add_f32 v[88:89], v[88:89], v[104:105]
	v_pk_add_f32 v[86:87], v[86:87], v[114:115]
	v_pk_add_f32 v[92:93], v[92:93], v[102:103]
	v_pk_add_f32 v[90:91], v[90:91], v[112:113]
	v_pk_add_f32 v[100:101], v[84:85], v[106:107]
	v_pk_add_f32 v[102:103], v[82:83], v[116:117]
	v_mul_f32_e32 v84, v95, v95
	v_mul_f32_e32 v85, v97, v97
	v_mul_f32_e32 v104, v87, v87
	v_mul_f32_e32 v105, v89, v89
	v_cvt_pk_bf16_f32 v82, v94, v95
	v_mul_f32_e32 v95, v91, v91
	v_mul_f32_e32 v106, v103, v103
	v_fmac_f32_e32 v84, v94, v94
	v_fmac_f32_e32 v85, v96, v96
	v_fmac_f32_e32 v104, v86, v86
	v_fmac_f32_e32 v105, v88, v88
	v_cvt_pk_bf16_f32 v83, v96, v97
	v_mul_f32_e32 v97, v93, v93
	v_mul_f32_e32 v107, v101, v101
	v_fmac_f32_e32 v95, v90, v90
	v_fmac_f32_e32 v106, v102, v102
	v_add_f32_e32 v84, v84, v85
	v_add_f32_e32 v85, v104, v105
	v_fmac_f32_e32 v97, v92, v92
	v_fmac_f32_e32 v107, v100, v100
	v_add_f32_e32 v84, v95, v84
	v_add_f32_e32 v85, v106, v85
	v_add_f32_e32 v84, v97, v84
	v_add_f32_e32 v85, v107, v85
	v_add_f32_e32 v94, v84, v85
	ds_bpermute_b32 v95, v160, v94
	v_cvt_pk_bf16_f32 v84, v90, v91
	v_cvt_pk_bf16_f32 v85, v92, v93
	global_store_dwordx4 v[108:109], v[82:85], off
	s_waitcnt lgkmcnt(0)
	s_nop 0
	v_add_f32_e32 v82, v94, v95
	ds_bpermute_b32 v83, v159, v82
	v_cvt_pk_bf16_f32 v84, v86, v87
	v_cvt_pk_bf16_f32 v85, v88, v89
	v_cvt_pk_bf16_f32 v86, v102, v103
	v_cvt_pk_bf16_f32 v87, v100, v101
	global_store_dwordx4 v[108:109], v[84:87], off offset:256
	s_and_saveexec_b64 s[24:25], s[2:3]
	s_cbranch_execz .LBB0_1339
	v_lshl_add_u64 v[84:85], v[98:99], 2, s[6:7]
	s_waitcnt lgkmcnt(0)
	v_add_f32_e32 v82, v82, v83
	global_atomic_add_f32 v[84:85], v82, off
; __device__ __forceinline__ unsigned cvtpk(float lo, float hi) { f32x2_t v = {lo, hi}; bf16x2_t b = __builtin_convertvector(v, bf16x2_t); return __builtin_bit_cast(unsigned, b); }
; __device__ __forceinline__ float bflo(unsigned w) { return __uint_as_float(w << 16); }
; __device__ __forceinline__ float bfhi(unsigned w) { return __uint_as_float(w & 0xffff0000u); }
;     __device__ __forceinline__ void operator()(const f32x4 (&acc)[2][2][4][2], const Unit& u, int wr, int wc, int fr, int fq) const {
;     ...
;                 const int row = row0 + ai * 128 + m * 16; float s = 0.f;
; #pragma unroll
;                 for (int bj = 0; bj < 2; ++bj) {
;                     const size_t off = (size_t)row * D + col0 + bj * 128;
;                     f32x4 b0, b1;
;                     if (BASE_F32) { b0 = __builtin_nontemporal_load((const f32x4*)(base + off)); b1 = __builtin_nontemporal_load((const f32x4*)(base + off + 4)); }
;                     else { const u32x4 w = *(const u32x4*)(xb + off); b0 = (f32x4){bflo(w.x), bfhi(w.x), bflo(w.y), bfhi(w.y)}; b1 = (f32x4){bflo(w.z), bfhi(w.z), bflo(w.w), bfhi(w.w)}; }
;                     const f32x4 h0 = b0 + acc[ai][bj][m][0] * scale, h1 = b1 + acc[ai][bj][m][1] * scale;
;                     if (OUT_F32) { *(f32x4*)(out + off) = h0; *(f32x4*)(out + off + 4) = h1; }
;                     else { u32x4 w; w.x = cvtpk(h0[0], h0[1]); w.y = cvtpk(h0[2], h0[3]); w.z = cvtpk(h1[0], h1[1]); w.w = cvtpk(h1[2], h1[3]); st16(xb + off, w); }
;                     s += (h0[0] * h0[0] + h0[1] * h0[1]) + (h0[2] * h0[2] + h0[3] * h0[3]) + (h1[0] * h1[0] + h1[1] * h1[1]) + (h1[2] * h1[2] + h1[3] * h1[3]);
;                 }
;                 s += __shfl_xor(s, 16); s += __shfl_xor(s, 32);
;                 if (fq == 0) __hip_atomic_fetch_add(ssq_out + row, s, __ATOMIC_RELAXED, __HIP_MEMORY_SCOPE_AGENT);
.LBB0_1339:
	s_or_b64 exec, exec, s[24:25]
	v_or_b32_e32 v82, 48, v148
	s_waitcnt lgkmcnt(0)
	v_ashrrev_i32_e32 v83, 31, v82
	v_lshlrev_b64 v[84:85], 12, v[82:83]
	v_lshl_add_u64 v[84:85], s[36:37], 0, v[84:85]
	v_lshl_add_u64 v[92:93], v[84:85], 0, v[138:139]
	s_waitcnt vmcnt(15)
	v_lshlrev_b32_e32 v94, 16, v204
	v_and_b32_e32 v95, 0xffff0000, v204
	v_lshlrev_b32_e32 v84, 16, v205
	v_and_b32_e32 v85, 0xffff0000, v205
	s_waitcnt vmcnt(14)
	v_lshlrev_b32_e32 v98, 16, v208
	v_and_b32_e32 v99, 0xffff0000, v208
	v_lshlrev_b32_e32 v88, 16, v209
	v_and_b32_e32 v89, 0xffff0000, v209
	v_lshlrev_b32_e32 v96, 16, v206
	v_and_b32_e32 v97, 0xffff0000, v206
	v_lshlrev_b32_e32 v86, 16, v207
	v_and_b32_e32 v87, 0xffff0000, v207
	v_lshlrev_b32_e32 v100, 16, v210
	v_and_b32_e32 v101, 0xffff0000, v210
	v_lshlrev_b32_e32 v90, 16, v211
	v_and_b32_e32 v91, 0xffff0000, v211
	v_pk_add_f32 v[80:81], v[80:81], v[84:85]
	v_pk_add_f32 v[78:79], v[78:79], v[94:95]
	v_pk_add_f32 v[72:73], v[72:73], v[88:89]
	v_pk_add_f32 v[70:71], v[70:71], v[98:99]
	v_pk_add_f32 v[76:77], v[76:77], v[86:87]
	v_pk_add_f32 v[74:75], v[74:75], v[96:97]
	v_pk_add_f32 v[84:85], v[68:69], v[90:91]
	v_pk_add_f32 v[86:87], v[66:67], v[100:101]
	v_mul_f32_e32 v68, v79, v79
	v_mul_f32_e32 v69, v81, v81
	v_mul_f32_e32 v88, v71, v71
	v_mul_f32_e32 v89, v73, v73
	v_cvt_pk_bf16_f32 v66, v78, v79
	v_mul_f32_e32 v79, v75, v75
	v_mul_f32_e32 v90, v87, v87
	v_fmac_f32_e32 v68, v78, v78
	v_fmac_f32_e32 v69, v80, v80
	v_fmac_f32_e32 v88, v70, v70
	v_fmac_f32_e32 v89, v72, v72
	v_cvt_pk_bf16_f32 v67, v80, v81
	v_mul_f32_e32 v81, v77, v77
	v_mul_f32_e32 v91, v85, v85
	v_fmac_f32_e32 v79, v74, v74
	v_fmac_f32_e32 v90, v86, v86
	v_add_f32_e32 v68, v68, v69
	v_add_f32_e32 v69, v88, v89
	v_fmac_f32_e32 v81, v76, v76
	v_fmac_f32_e32 v91, v84, v84
	v_add_f32_e32 v68, v79, v68
	v_add_f32_e32 v69, v90, v69
	v_add_f32_e32 v68, v81, v68
	v_add_f32_e32 v69, v91, v69
	v_add_f32_e32 v78, v68, v69
	ds_bpermute_b32 v79, v160, v78
	v_cvt_pk_bf16_f32 v68, v74, v75
	v_cvt_pk_bf16_f32 v69, v76, v77
	global_store_dwordx4 v[92:93], v[66:69], off
	s_waitcnt lgkmcnt(0)
	s_nop 0
	v_add_f32_e32 v66, v78, v79
	ds_bpermute_b32 v67, v159, v66
	v_cvt_pk_bf16_f32 v68, v70, v71
	v_cvt_pk_bf16_f32 v69, v72, v73
	v_cvt_pk_bf16_f32 v70, v86, v87
	v_cvt_pk_bf16_f32 v71, v84, v85
	global_store_dwordx4 v[92:93], v[68:71], off offset:256
	s_and_saveexec_b64 s[24:25], s[2:3]
	s_cbranch_execz .LBB0_1341
	v_lshl_add_u64 v[68:69], v[82:83], 2, s[6:7]
	s_waitcnt lgkmcnt(0)
	v_add_f32_e32 v66, v66, v67
	global_atomic_add_f32 v[68:69], v66, off
.LBB0_1341:
	s_or_b64 exec, exec, s[24:25]
	v_add_u32_e32 v66, 0x80, v148
	s_waitcnt lgkmcnt(0)
	v_ashrrev_i32_e32 v67, 31, v66
	v_lshlrev_b64 v[68:69], 12, v[66:67]
	v_lshl_add_u64 v[68:69], s[36:37], 0, v[68:69]
	v_lshl_add_u64 v[76:77], v[68:69], 0, v[138:139]
	s_waitcnt vmcnt(15)
	v_lshlrev_b32_e32 v78, 16, v212
	v_and_b32_e32 v79, 0xffff0000, v212
	v_lshlrev_b32_e32 v68, 16, v213
	v_and_b32_e32 v69, 0xffff0000, v213
	s_waitcnt vmcnt(14)
	v_lshlrev_b32_e32 v82, 16, v216
	v_and_b32_e32 v83, 0xffff0000, v216
	v_lshlrev_b32_e32 v72, 16, v217
	v_and_b32_e32 v73, 0xffff0000, v217
	v_lshlrev_b32_e32 v80, 16, v214
	v_and_b32_e32 v81, 0xffff0000, v214
	v_lshlrev_b32_e32 v70, 16, v215
	v_and_b32_e32 v71, 0xffff0000, v215
	v_lshlrev_b32_e32 v84, 16, v218
	v_and_b32_e32 v85, 0xffff0000, v218
	v_lshlrev_b32_e32 v74, 16, v219
	v_and_b32_e32 v75, 0xffff0000, v219
	v_pk_add_f32 v[64:65], v[64:65], v[68:69]
	v_pk_add_f32 v[62:63], v[62:63], v[78:79]
	v_pk_add_f32 v[56:57], v[56:57], v[72:73]
	v_pk_add_f32 v[54:55], v[54:55], v[82:83]
	v_pk_add_f32 v[60:61], v[60:61], v[70:71]
	v_pk_add_f32 v[58:59], v[58:59], v[80:81]
	v_pk_add_f32 v[68:69], v[52:53], v[74:75]
	v_pk_add_f32 v[70:71], v[50:51], v[84:85]
	v_mul_f32_e32 v52, v63, v63
	v_mul_f32_e32 v53, v65, v65
	v_mul_f32_e32 v72, v55, v55
	v_mul_f32_e32 v73, v57, v57
	v_cvt_pk_bf16_f32 v50, v62, v63
	v_mul_f32_e32 v63, v59, v59
	v_mul_f32_e32 v74, v71, v71
	v_fmac_f32_e32 v52, v62, v62
	v_fmac_f32_e32 v53, v64, v64
	v_fmac_f32_e32 v72, v54, v54
	v_fmac_f32_e32 v73, v56, v56
	v_cvt_pk_bf16_f32 v51, v64, v65
	v_mul_f32_e32 v65, v61, v61
	v_mul_f32_e32 v75, v69, v69
	v_fmac_f32_e32 v63, v58, v58
	v_fmac_f32_e32 v74, v70, v70
	v_add_f32_e32 v52, v52, v53
	v_add_f32_e32 v53, v72, v73
	v_fmac_f32_e32 v65, v60, v60
	v_fmac_f32_e32 v75, v68, v68
	v_add_f32_e32 v52, v63, v52
	v_add_f32_e32 v53, v74, v53
	v_add_f32_e32 v52, v65, v52
	v_add_f32_e32 v53, v75, v53
	v_add_f32_e32 v62, v52, v53
	ds_bpermute_b32 v63, v160, v62
	v_cvt_pk_bf16_f32 v52, v58, v59
	v_cvt_pk_bf16_f32 v53, v60, v61
	global_store_dwordx4 v[76:77], v[50:53], off
	s_waitcnt lgkmcnt(0)
	s_nop 0
	v_add_f32_e32 v50, v62, v63
	ds_bpermute_b32 v51, v159, v50
	v_cvt_pk_bf16_f32 v52, v54, v55
	v_cvt_pk_bf16_f32 v53, v56, v57
	v_cvt_pk_bf16_f32 v54, v70, v71
	v_cvt_pk_bf16_f32 v55, v68, v69
	global_store_dwordx4 v[76:77], v[52:55], off offset:256
	s_and_saveexec_b64 s[24:25], s[2:3]
	s_cbranch_execz .LBB0_1343
	v_lshl_add_u64 v[52:53], v[66:67], 2, s[6:7]
	s_waitcnt lgkmcnt(0)
	v_add_f32_e32 v50, v50, v51
	global_atomic_add_f32 v[52:53], v50, off
; __device__ __forceinline__ unsigned cvtpk(float lo, float hi) { f32x2_t v = {lo, hi}; bf16x2_t b = __builtin_convertvector(v, bf16x2_t); return __builtin_bit_cast(unsigned, b); }
; __device__ __forceinline__ float bflo(unsigned w) { return __uint_as_float(w << 16); }
; __device__ __forceinline__ float bfhi(unsigned w) { return __uint_as_float(w & 0xffff0000u); }
;     __device__ __forceinline__ void operator()(const f32x4 (&acc)[2][2][4][2], const Unit& u, int wr, int wc, int fr, int fq) const {
;     ...
;                 const int row = row0 + ai * 128 + m * 16; float s = 0.f;
; #pragma unroll
;                 for (int bj = 0; bj < 2; ++bj) {
;                     const size_t off = (size_t)row * D + col0 + bj * 128;
;                     f32x4 b0, b1;
;                     if (BASE_F32) { b0 = __builtin_nontemporal_load((const f32x4*)(base + off)); b1 = __builtin_nontemporal_load((const f32x4*)(base + off + 4)); }
;                     else { const u32x4 w = *(const u32x4*)(xb + off); b0 = (f32x4){bflo(w.x), bfhi(w.x), bflo(w.y), bfhi(w.y)}; b1 = (f32x4){bflo(w.z), bfhi(w.z), bflo(w.w), bfhi(w.w)}; }
;                     const f32x4 h0 = b0 + acc[ai][bj][m][0] * scale, h1 = b1 + acc[ai][bj][m][1] * scale;
;                     if (OUT_F32) { *(f32x4*)(out + off) = h0; *(f32x4*)(out + off + 4) = h1; }
;                     else { u32x4 w; w.x = cvtpk(h0[0], h0[1]); w.y = cvtpk(h0[2], h0[3]); w.z = cvtpk(h1[0], h1[1]); w.w = cvtpk(h1[2], h1[3]); st16(xb + off, w); }
;                     s += (h0[0] * h0[0] + h0[1] * h0[1]) + (h0[2] * h0[2] + h0[3] * h0[3]) + (h1[0] * h1[0] + h1[1] * h1[1]) + (h1[2] * h1[2] + h1[3] * h1[3]);
;                 }
;                 s += __shfl_xor(s, 16); s += __shfl_xor(s, 32);
;                 if (fq == 0) __hip_atomic_fetch_add(ssq_out + row, s, __ATOMIC_RELAXED, __HIP_MEMORY_SCOPE_AGENT);
.LBB0_1343:
	s_or_b64 exec, exec, s[24:25]
	v_add_u32_e32 v50, 0x90, v148
	s_waitcnt lgkmcnt(0)
	v_ashrrev_i32_e32 v51, 31, v50
	v_lshlrev_b64 v[52:53], 12, v[50:51]
	v_lshl_add_u64 v[52:53], s[36:37], 0, v[52:53]
	v_lshl_add_u64 v[60:61], v[52:53], 0, v[138:139]
	s_waitcnt vmcnt(15)
	v_lshlrev_b32_e32 v62, 16, v220
	v_and_b32_e32 v63, 0xffff0000, v220
	v_lshlrev_b32_e32 v52, 16, v221
	v_and_b32_e32 v53, 0xffff0000, v221
	s_waitcnt vmcnt(14)
	v_lshlrev_b32_e32 v66, 16, v224
	v_and_b32_e32 v67, 0xffff0000, v224
	v_lshlrev_b32_e32 v56, 16, v225
	v_and_b32_e32 v57, 0xffff0000, v225
	v_lshlrev_b32_e32 v64, 16, v222
	v_and_b32_e32 v65, 0xffff0000, v222
	v_lshlrev_b32_e32 v54, 16, v223
	v_and_b32_e32 v55, 0xffff0000, v223
	v_lshlrev_b32_e32 v68, 16, v226
	v_and_b32_e32 v69, 0xffff0000, v226
	v_lshlrev_b32_e32 v58, 16, v227
	v_and_b32_e32 v59, 0xffff0000, v227
	v_pk_add_f32 v[48:49], v[48:49], v[52:53]
	v_pk_add_f32 v[46:47], v[46:47], v[62:63]
	v_pk_add_f32 v[40:41], v[40:41], v[56:57]
	v_pk_add_f32 v[38:39], v[38:39], v[66:67]
	v_pk_add_f32 v[44:45], v[44:45], v[54:55]
	v_pk_add_f32 v[42:43], v[42:43], v[64:65]
	v_pk_add_f32 v[52:53], v[36:37], v[58:59]
	v_pk_add_f32 v[54:55], v[34:35], v[68:69]
	v_mul_f32_e32 v36, v47, v47
	v_mul_f32_e32 v37, v49, v49
	v_mul_f32_e32 v56, v39, v39
	v_mul_f32_e32 v57, v41, v41
	v_cvt_pk_bf16_f32 v34, v46, v47
	v_mul_f32_e32 v47, v43, v43
	v_mul_f32_e32 v58, v55, v55
	v_fmac_f32_e32 v36, v46, v46
	v_fmac_f32_e32 v37, v48, v48
	v_fmac_f32_e32 v56, v38, v38
	v_fmac_f32_e32 v57, v40, v40
	v_cvt_pk_bf16_f32 v35, v48, v49
	v_mul_f32_e32 v49, v45, v45
	v_mul_f32_e32 v59, v53, v53
	v_fmac_f32_e32 v47, v42, v42
	v_fmac_f32_e32 v58, v54, v54
	v_add_f32_e32 v36, v36, v37
	v_add_f32_e32 v37, v56, v57
	v_fmac_f32_e32 v49, v44, v44
	v_fmac_f32_e32 v59, v52, v52
	v_add_f32_e32 v36, v47, v36
	v_add_f32_e32 v37, v58, v37
	v_add_f32_e32 v36, v49, v36
	v_add_f32_e32 v37, v59, v37
	v_add_f32_e32 v46, v36, v37
	ds_bpermute_b32 v47, v160, v46
	v_cvt_pk_bf16_f32 v36, v42, v43
	v_cvt_pk_bf16_f32 v37, v44, v45
	global_store_dwordx4 v[60:61], v[34:37], off
	s_waitcnt lgkmcnt(0)
	s_nop 0
	v_add_f32_e32 v34, v46, v47
	ds_bpermute_b32 v35, v159, v34
	v_cvt_pk_bf16_f32 v36, v38, v39
	v_cvt_pk_bf16_f32 v37, v40, v41
	v_cvt_pk_bf16_f32 v38, v54, v55
	v_cvt_pk_bf16_f32 v39, v52, v53
	global_store_dwordx4 v[60:61], v[36:39], off offset:256
	s_and_saveexec_b64 s[24:25], s[2:3]
	s_cbranch_execz .LBB0_1345
	v_lshl_add_u64 v[36:37], v[50:51], 2, s[6:7]
	s_waitcnt lgkmcnt(0)
	v_add_f32_e32 v34, v34, v35
	global_atomic_add_f32 v[36:37], v34, off
; __device__ __forceinline__ unsigned cvtpk(float lo, float hi) { f32x2_t v = {lo, hi}; bf16x2_t b = __builtin_convertvector(v, bf16x2_t); return __builtin_bit_cast(unsigned, b); }
; __device__ __forceinline__ float bflo(unsigned w) { return __uint_as_float(w << 16); }
; __device__ __forceinline__ float bfhi(unsigned w) { return __uint_as_float(w & 0xffff0000u); }
;     __device__ __forceinline__ void operator()(const f32x4 (&acc)[2][2][4][2], const Unit& u, int wr, int wc, int fr, int fq) const {
;     ...
;                 const int row = row0 + ai * 128 + m * 16; float s = 0.f;
; #pragma unroll
;                 for (int bj = 0; bj < 2; ++bj) {
;                     const size_t off = (size_t)row * D + col0 + bj * 128;
;                     f32x4 b0, b1;
;                     if (BASE_F32) { b0 = __builtin_nontemporal_load((const f32x4*)(base + off)); b1 = __builtin_nontemporal_load((const f32x4*)(base + off + 4)); }
;                     else { const u32x4 w = *(const u32x4*)(xb + off); b0 = (f32x4){bflo(w.x), bfhi(w.x), bflo(w.y), bfhi(w.y)}; b1 = (f32x4){bflo(w.z), bfhi(w.z), bflo(w.w), bfhi(w.w)}; }
;                     const f32x4 h0 = b0 + acc[ai][bj][m][0] * scale, h1 = b1 + acc[ai][bj][m][1] * scale;
;                     if (OUT_F32) { *(f32x4*)(out + off) = h0; *(f32x4*)(out + off + 4) = h1; }
;                     else { u32x4 w; w.x = cvtpk(h0[0], h0[1]); w.y = cvtpk(h0[2], h0[3]); w.z = cvtpk(h1[0], h1[1]); w.w = cvtpk(h1[2], h1[3]); st16(xb + off, w); }
;                     s += (h0[0] * h0[0] + h0[1] * h0[1]) + (h0[2] * h0[2] + h0[3] * h0[3]) + (h1[0] * h1[0] + h1[1] * h1[1]) + (h1[2] * h1[2] + h1[3] * h1[3]);
;                 }
;                 s += __shfl_xor(s, 16); s += __shfl_xor(s, 32);
;                 if (fq == 0) __hip_atomic_fetch_add(ssq_out + row, s, __ATOMIC_RELAXED, __HIP_MEMORY_SCOPE_AGENT);
.LBB0_1345:
	s_or_b64 exec, exec, s[24:25]
	v_add_u32_e32 v34, 0xa0, v148
	s_waitcnt lgkmcnt(0)
	v_ashrrev_i32_e32 v35, 31, v34
	v_lshlrev_b64 v[36:37], 12, v[34:35]
	v_lshl_add_u64 v[36:37], s[36:37], 0, v[36:37]
	v_lshl_add_u64 v[44:45], v[36:37], 0, v[138:139]
	s_waitcnt vmcnt(15)
	v_lshlrev_b32_e32 v46, 16, v228
	v_and_b32_e32 v47, 0xffff0000, v228
	v_lshlrev_b32_e32 v36, 16, v229
	v_and_b32_e32 v37, 0xffff0000, v229
	s_waitcnt vmcnt(14)
	v_lshlrev_b32_e32 v50, 16, v232
	v_and_b32_e32 v51, 0xffff0000, v232
	v_lshlrev_b32_e32 v40, 16, v233
	v_and_b32_e32 v41, 0xffff0000, v233
	v_lshlrev_b32_e32 v48, 16, v230
	v_and_b32_e32 v49, 0xffff0000, v230
	v_lshlrev_b32_e32 v38, 16, v231
	v_and_b32_e32 v39, 0xffff0000, v231
	v_lshlrev_b32_e32 v52, 16, v234
	v_and_b32_e32 v53, 0xffff0000, v234
	v_lshlrev_b32_e32 v42, 16, v235
	v_and_b32_e32 v43, 0xffff0000, v235
	v_pk_add_f32 v[32:33], v[32:33], v[36:37]
	v_pk_add_f32 v[30:31], v[30:31], v[46:47]
	v_pk_add_f32 v[24:25], v[24:25], v[40:41]
	v_pk_add_f32 v[22:23], v[22:23], v[50:51]
	v_pk_add_f32 v[28:29], v[28:29], v[38:39]
	v_pk_add_f32 v[26:27], v[26:27], v[48:49]
	v_pk_add_f32 v[36:37], v[20:21], v[42:43]
	v_pk_add_f32 v[38:39], v[18:19], v[52:53]
	v_mul_f32_e32 v20, v31, v31
	v_mul_f32_e32 v21, v33, v33
	v_mul_f32_e32 v40, v23, v23
	v_mul_f32_e32 v41, v25, v25
	v_cvt_pk_bf16_f32 v18, v30, v31
	v_mul_f32_e32 v31, v27, v27
	v_mul_f32_e32 v42, v39, v39
	v_fmac_f32_e32 v20, v30, v30
	v_fmac_f32_e32 v21, v32, v32
	v_fmac_f32_e32 v40, v22, v22
	v_fmac_f32_e32 v41, v24, v24
	v_cvt_pk_bf16_f32 v19, v32, v33
	v_mul_f32_e32 v33, v29, v29
	v_mul_f32_e32 v43, v37, v37
	v_fmac_f32_e32 v31, v26, v26
	v_fmac_f32_e32 v42, v38, v38
	v_add_f32_e32 v20, v20, v21
	v_add_f32_e32 v21, v40, v41
	v_fmac_f32_e32 v33, v28, v28
	v_fmac_f32_e32 v43, v36, v36
	v_add_f32_e32 v20, v31, v20
	v_add_f32_e32 v21, v42, v21
	v_add_f32_e32 v20, v33, v20
	v_add_f32_e32 v21, v43, v21
	v_add_f32_e32 v30, v20, v21
	ds_bpermute_b32 v31, v160, v30
	v_cvt_pk_bf16_f32 v20, v26, v27
	v_cvt_pk_bf16_f32 v21, v28, v29
	global_store_dwordx4 v[44:45], v[18:21], off
	s_waitcnt lgkmcnt(0)
	s_nop 0
	v_add_f32_e32 v18, v30, v31
	ds_bpermute_b32 v19, v159, v18
	v_cvt_pk_bf16_f32 v20, v22, v23
	v_cvt_pk_bf16_f32 v21, v24, v25
	v_cvt_pk_bf16_f32 v22, v38, v39
	v_cvt_pk_bf16_f32 v23, v36, v37
	global_store_dwordx4 v[44:45], v[20:23], off offset:256
	s_and_saveexec_b64 s[24:25], s[2:3]
	s_cbranch_execz .LBB0_1347
	v_lshl_add_u64 v[20:21], v[34:35], 2, s[6:7]
	s_waitcnt lgkmcnt(0)
	v_add_f32_e32 v18, v18, v19
	global_atomic_add_f32 v[20:21], v18, off
.LBB0_1347:
	s_or_b64 exec, exec, s[24:25]
	v_add_u32_e32 v18, 0xb0, v148
	s_waitcnt lgkmcnt(0)
	v_ashrrev_i32_e32 v19, 31, v18
	v_lshlrev_b64 v[20:21], 12, v[18:19]
	v_lshl_add_u64 v[20:21], s[36:37], 0, v[20:21]
	v_lshl_add_u64 v[28:29], v[20:21], 0, v[138:139]
	s_waitcnt vmcnt(13)
	v_lshlrev_b32_e32 v30, 16, v184
	v_and_b32_e32 v31, 0xffff0000, v184
	v_lshlrev_b32_e32 v20, 16, v185
	v_and_b32_e32 v21, 0xffff0000, v185
	s_waitcnt vmcnt(12)
	v_lshlrev_b32_e32 v34, 16, v192
	v_and_b32_e32 v35, 0xffff0000, v192
	v_lshlrev_b32_e32 v24, 16, v193
	v_and_b32_e32 v25, 0xffff0000, v193
	v_lshlrev_b32_e32 v32, 16, v186
	v_and_b32_e32 v33, 0xffff0000, v186
	v_lshlrev_b32_e32 v22, 16, v187
	v_and_b32_e32 v23, 0xffff0000, v187
	v_lshlrev_b32_e32 v36, 16, v194
	v_and_b32_e32 v37, 0xffff0000, v194
	v_lshlrev_b32_e32 v26, 16, v195
	v_and_b32_e32 v27, 0xffff0000, v195
	v_pk_add_f32 v[16:17], v[16:17], v[20:21]
	v_pk_add_f32 v[14:15], v[14:15], v[30:31]
	v_pk_add_f32 v[8:9], v[8:9], v[24:25]
	v_pk_add_f32 v[6:7], v[6:7], v[34:35]
	v_pk_add_f32 v[12:13], v[12:13], v[22:23]
	v_pk_add_f32 v[10:11], v[10:11], v[32:33]
	v_pk_add_f32 v[20:21], v[4:5], v[26:27]
	v_pk_add_f32 v[22:23], v[2:3], v[36:37]
	v_mul_f32_e32 v4, v15, v15
	v_mul_f32_e32 v5, v17, v17
	v_mul_f32_e32 v24, v7, v7
	v_mul_f32_e32 v25, v9, v9
	v_cvt_pk_bf16_f32 v2, v14, v15
	v_mul_f32_e32 v15, v11, v11
	v_mul_f32_e32 v26, v23, v23
	v_fmac_f32_e32 v4, v14, v14
	v_fmac_f32_e32 v5, v16, v16
	v_fmac_f32_e32 v24, v6, v6
	v_fmac_f32_e32 v25, v8, v8
	v_cvt_pk_bf16_f32 v3, v16, v17
	v_mul_f32_e32 v17, v13, v13
	v_mul_f32_e32 v27, v21, v21
	v_fmac_f32_e32 v15, v10, v10
	v_fmac_f32_e32 v26, v22, v22
	v_add_f32_e32 v4, v4, v5
	v_add_f32_e32 v5, v24, v25
	v_fmac_f32_e32 v17, v12, v12
	v_fmac_f32_e32 v27, v20, v20
	v_add_f32_e32 v4, v15, v4
	v_add_f32_e32 v5, v26, v5
	v_add_f32_e32 v4, v17, v4
	v_add_f32_e32 v5, v27, v5
	v_add_f32_e32 v14, v4, v5
	ds_bpermute_b32 v15, v160, v14
	v_cvt_pk_bf16_f32 v4, v10, v11
	v_cvt_pk_bf16_f32 v5, v12, v13
	global_store_dwordx4 v[28:29], v[2:5], off
	s_waitcnt lgkmcnt(0)
	s_nop 0
	v_add_f32_e32 v2, v14, v15
	ds_bpermute_b32 v3, v159, v2
	v_cvt_pk_bf16_f32 v4, v6, v7
	v_cvt_pk_bf16_f32 v5, v8, v9
	v_cvt_pk_bf16_f32 v6, v22, v23
	v_cvt_pk_bf16_f32 v7, v20, v21
	global_store_dwordx4 v[28:29], v[4:7], off offset:256
	s_and_saveexec_b64 s[24:25], s[2:3]
	s_cbranch_execz .LBB0_1349
	v_lshl_add_u64 v[4:5], v[18:19], 2, s[6:7]
	s_waitcnt lgkmcnt(0)
	v_add_f32_e32 v2, v2, v3
	global_atomic_add_f32 v[4:5], v2, off

; __device__ __forceinline__ unsigned cvtpk(float lo, float hi) { f32x2_t v = {lo, hi}; bf16x2_t b = __builtin_convertvector(v, bf16x2_t); return __builtin_bit_cast(unsigned, b); }
; __device__ __forceinline__ float bflo(unsigned w) { return __uint_as_float(w << 16); }
; __device__ __forceinline__ float bfhi(unsigned w) { return __uint_as_float(w & 0xffff0000u); }
;     __device__ __forceinline__ void operator()(const f32x4 (&acc)[2][2][4][2], const Unit& u, int wr, int wc, int fr, int fq) const {
;         const int row0 = u.pm * 256 + wr * 64 + fr, col0 = (u.pn & 7) * 256 + wc * 32 + 8 * fq;
; #pragma unroll
;         for (int ai = 0; ai < 2; ++ai)
; #pragma unroll
;             for (int m = 0; m < 4; ++m) {
;                 const int row = row0 + ai * 128 + m * 16; float s = 0.f;
; #pragma unroll
;                 for (int bj = 0; bj < 2; ++bj) {
;                     const size_t off = (size_t)row * D + col0 + bj * 128;
;                     f32x4 b0, b1;
;                     if (BASE_F32) { b0 = __builtin_nontemporal_load((const f32x4*)(base + off)); b1 = __builtin_nontemporal_load((const f32x4*)(base + off + 4)); }
;                     else { const u32x4 w = *(const u32x4*)(xb + off); b0 = (f32x4){bflo(w.x), bfhi(w.x), bflo(w.y), bfhi(w.y)}; b1 = (f32x4){bflo(w.z), bfhi(w.z), bflo(w.w), bfhi(w.w)}; }
;                     const f32x4 h0 = b0 + acc[ai][bj][m][0] * scale, h1 = b1 + acc[ai][bj][m][1] * scale;
;                     if (OUT_F32) { *(f32x4*)(out + off) = h0; *(f32x4*)(out + off + 4) = h1; }
;                     else { u32x4 w; w.x = cvtpk(h0[0], h0[1]); w.y = cvtpk(h0[2], h0[3]); w.z = cvtpk(h1[0], h1[1]); w.w = cvtpk(h1[2], h1[3]); st16(xb + off, w); }
;                     s += (h0[0] * h0[0] + h0[1] * h0[1]) + (h0[2] * h0[2] + h0[3] * h0[3]) + (h1[0] * h1[0] + h1[1] * h1[1]) + (h1[2] * h1[2] + h1[3] * h1[3]);
;                 }
;                 s += __shfl_xor(s, 16); s += __shfl_xor(s, 32);
;                 if (fq == 0) __hip_atomic_fetch_add(ssq_out + row, s, __ATOMIC_RELAXED, __HIP_MEMORY_SCOPE_AGENT);
.LBB0_1607:
	v_lshl_add_u32 v148, s24, 8, v150
	s_lshl_b32 s17, s26, 8
	s_and_b32 s17, s17, 0x700
	v_ashrrev_i32_e32 v149, 31, v148
	v_or_b32_e32 v138, s17, v152
	v_lshlrev_b64 v[158:159], 12, v[148:149]
	v_lshl_add_u64 v[158:159], s[36:37], 0, v[158:159]
	v_lshlrev_b32_e32 v138, 1, v138
	v_lshl_add_u64 v[168:169], v[158:159], 0, v[138:139]
	global_load_dwordx4 v[160:163], v[168:169], off
	global_load_dwordx4 v[164:167], v[168:169], off offset:256
	v_or_b32_e32 v178, 16, v148
	v_ashrrev_i32_e32 v179, 31, v178
	v_lshlrev_b64 v[178:179], 12, v[178:179]
	v_lshl_add_u64 v[178:179], s[36:37], 0, v[178:179]
	v_lshl_add_u64 v[178:179], v[178:179], 0, v[138:139]
	global_load_dwordx4 v[180:183], v[178:179], off
	global_load_dwordx4 v[184:187], v[178:179], off offset:256
	v_or_b32_e32 v178, 32, v148
	v_ashrrev_i32_e32 v179, 31, v178
	v_lshlrev_b64 v[178:179], 12, v[178:179]
	v_lshl_add_u64 v[178:179], s[36:37], 0, v[178:179]
	v_lshl_add_u64 v[178:179], v[178:179], 0, v[138:139]
	global_load_dwordx4 v[192:195], v[178:179], off
	global_load_dwordx4 v[196:199], v[178:179], off offset:256
	v_or_b32_e32 v178, 48, v148
	v_ashrrev_i32_e32 v179, 31, v178
	v_lshlrev_b64 v[178:179], 12, v[178:179]
	v_lshl_add_u64 v[178:179], s[36:37], 0, v[178:179]
	v_lshl_add_u64 v[178:179], v[178:179], 0, v[138:139]
	global_load_dwordx4 v[200:203], v[178:179], off
	global_load_dwordx4 v[204:207], v[178:179], off offset:256
	v_add_u32_e32 v178, 0x80, v148
	v_ashrrev_i32_e32 v179, 31, v178
	v_lshlrev_b64 v[178:179], 12, v[178:179]
	v_lshl_add_u64 v[178:179], s[36:37], 0, v[178:179]
	v_lshl_add_u64 v[178:179], v[178:179], 0, v[138:139]
	global_load_dwordx4 v[208:211], v[178:179], off
	global_load_dwordx4 v[212:215], v[178:179], off offset:256
	v_add_u32_e32 v178, 0x90, v148
	v_ashrrev_i32_e32 v179, 31, v178
	v_lshlrev_b64 v[178:179], 12, v[178:179]
	v_lshl_add_u64 v[178:179], s[36:37], 0, v[178:179]
	v_lshl_add_u64 v[178:179], v[178:179], 0, v[138:139]
	global_load_dwordx4 v[216:219], v[178:179], off
	global_load_dwordx4 v[220:223], v[178:179], off offset:256
	v_add_u32_e32 v178, 0xa0, v148
	v_ashrrev_i32_e32 v179, 31, v178
	v_lshlrev_b64 v[178:179], 12, v[178:179]
	v_lshl_add_u64 v[178:179], s[36:37], 0, v[178:179]
	v_lshl_add_u64 v[178:179], v[178:179], 0, v[138:139]
	global_load_dwordx4 v[224:227], v[178:179], off
	global_load_dwordx4 v[228:231], v[178:179], off offset:256
	v_and_b32_e32 v158, 64, v156
	v_xor_b32_e32 v157, 16, v156
	v_add_u32_e32 v158, 64, v158
	v_xor_b32_e32 v159, 32, v156
	v_cmp_lt_i32_e32 vcc, v157, v158
	s_waitcnt vmcnt(12)
	v_lshlrev_b32_e32 v170, 16, v160
	v_cndmask_b32_e32 v157, v156, v157, vcc
	v_cmp_lt_i32_e32 vcc, v159, v158
	v_and_b32_e32 v171, 0xffff0000, v160
	v_lshlrev_b32_e32 v160, 16, v161
	v_and_b32_e32 v161, 0xffff0000, v161
	v_lshlrev_b32_e32 v174, 16, v164
	v_and_b32_e32 v175, 0xffff0000, v164
	v_lshlrev_b32_e32 v164, 16, v165
	v_and_b32_e32 v165, 0xffff0000, v165
	v_cndmask_b32_e32 v159, v156, v159, vcc
	v_lshlrev_b32_e32 v172, 16, v162
	v_and_b32_e32 v173, 0xffff0000, v162
	v_lshlrev_b32_e32 v162, 16, v163
	v_and_b32_e32 v163, 0xffff0000, v163
	v_lshlrev_b32_e32 v176, 16, v166
	v_and_b32_e32 v177, 0xffff0000, v166
	v_lshlrev_b32_e32 v166, 16, v167
	v_and_b32_e32 v167, 0xffff0000, v167
	v_pk_add_f32 v[128:129], v[128:129], v[160:161]
	v_pk_add_f32 v[126:127], v[126:127], v[170:171]
	v_pk_add_f32 v[120:121], v[120:121], v[164:165]
	v_pk_add_f32 v[118:119], v[118:119], v[174:175]
	v_lshlrev_b32_e32 v158, 2, v157
	v_lshlrev_b32_e32 v157, 2, v159
	v_pk_add_f32 v[124:125], v[124:125], v[162:163]
	v_pk_add_f32 v[122:123], v[122:123], v[172:173]
	v_pk_add_f32 v[160:161], v[116:117], v[166:167]
	v_pk_add_f32 v[162:163], v[114:115], v[176:177]
	v_mul_f32_e32 v116, v127, v127
	v_mul_f32_e32 v117, v129, v129
	v_mul_f32_e32 v159, v119, v119
	v_mul_f32_e32 v164, v121, v121
	v_cvt_pk_bf16_f32 v114, v126, v127
	v_mul_f32_e32 v127, v123, v123
	v_mul_f32_e32 v165, v163, v163
	v_fmac_f32_e32 v116, v126, v126
	v_fmac_f32_e32 v117, v128, v128
	v_fmac_f32_e32 v159, v118, v118
	v_fmac_f32_e32 v164, v120, v120
	v_cvt_pk_bf16_f32 v115, v128, v129
	v_mul_f32_e32 v129, v125, v125
	v_mul_f32_e32 v166, v161, v161
	v_fmac_f32_e32 v127, v122, v122
	v_fmac_f32_e32 v165, v162, v162
	v_add_f32_e32 v116, v116, v117
	v_add_f32_e32 v117, v159, v164
	v_fmac_f32_e32 v129, v124, v124
	v_fmac_f32_e32 v166, v160, v160
	v_add_f32_e32 v116, v127, v116
	v_add_f32_e32 v117, v165, v117
	v_add_f32_e32 v116, v129, v116
	v_add_f32_e32 v117, v166, v117
	v_add_f32_e32 v126, v116, v117
	ds_bpermute_b32 v127, v158, v126
	v_cvt_pk_bf16_f32 v116, v122, v123
	v_cvt_pk_bf16_f32 v117, v124, v125
	global_store_dwordx4 v[168:169], v[114:117], off
	s_waitcnt lgkmcnt(0)
	s_nop 0
	v_add_f32_e32 v114, v126, v127
	ds_bpermute_b32 v115, v157, v114
	v_cvt_pk_bf16_f32 v116, v118, v119
	v_cvt_pk_bf16_f32 v117, v120, v121
	v_cvt_pk_bf16_f32 v118, v162, v163
	v_cvt_pk_bf16_f32 v119, v160, v161
	global_store_dwordx4 v[168:169], v[116:119], off offset:256
	s_and_saveexec_b64 s[24:25], s[2:3]
	s_cbranch_execz .LBB0_1609
	v_lshl_add_u64 v[116:117], v[148:149], 2, s[6:7]
	s_waitcnt lgkmcnt(0)
	v_add_f32_e32 v114, v114, v115
	global_atomic_add_f32 v[116:117], v114, off
; __device__ __forceinline__ unsigned cvtpk(float lo, float hi) { f32x2_t v = {lo, hi}; bf16x2_t b = __builtin_convertvector(v, bf16x2_t); return __builtin_bit_cast(unsigned, b); }
; __device__ __forceinline__ float bflo(unsigned w) { return __uint_as_float(w << 16); }
; __device__ __forceinline__ float bfhi(unsigned w) { return __uint_as_float(w & 0xffff0000u); }
;     __device__ __forceinline__ void operator()(const f32x4 (&acc)[2][2][4][2], const Unit& u, int wr, int wc, int fr, int fq) const {
;     ...
;                 const int row = row0 + ai * 128 + m * 16; float s = 0.f;
; #pragma unroll
;                 for (int bj = 0; bj < 2; ++bj) {
;                     const size_t off = (size_t)row * D + col0 + bj * 128;
;                     f32x4 b0, b1;
;                     if (BASE_F32) { b0 = __builtin_nontemporal_load((const f32x4*)(base + off)); b1 = __builtin_nontemporal_load((const f32x4*)(base + off + 4)); }
;                     else { const u32x4 w = *(const u32x4*)(xb + off); b0 = (f32x4){bflo(w.x), bfhi(w.x), bflo(w.y), bfhi(w.y)}; b1 = (f32x4){bflo(w.z), bfhi(w.z), bflo(w.w), bfhi(w.w)}; }
;                     const f32x4 h0 = b0 + acc[ai][bj][m][0] * scale, h1 = b1 + acc[ai][bj][m][1] * scale;
;                     if (OUT_F32) { *(f32x4*)(out + off) = h0; *(f32x4*)(out + off + 4) = h1; }
;                     else { u32x4 w; w.x = cvtpk(h0[0], h0[1]); w.y = cvtpk(h0[2], h0[3]); w.z = cvtpk(h1[0], h1[1]); w.w = cvtpk(h1[2], h1[3]); st16(xb + off, w); }
;                     s += (h0[0] * h0[0] + h0[1] * h0[1]) + (h0[2] * h0[2] + h0[3] * h0[3]) + (h1[0] * h1[0] + h1[1] * h1[1]) + (h1[2] * h1[2] + h1[3] * h1[3]);
;                 }
;                 s += __shfl_xor(s, 16); s += __shfl_xor(s, 32);
;                 if (fq == 0) __hip_atomic_fetch_add(ssq_out + row, s, __ATOMIC_RELAXED, __HIP_MEMORY_SCOPE_AGENT);
.LBB0_1609:
	s_or_b64 exec, exec, s[24:25]
	v_or_b32_e32 v114, 16, v148
	s_waitcnt lgkmcnt(0)
	v_ashrrev_i32_e32 v115, 31, v114
	v_lshlrev_b64 v[116:117], 12, v[114:115]
	v_lshl_add_u64 v[116:117], s[36:37], 0, v[116:117]
	v_lshl_add_u64 v[124:125], v[116:117], 0, v[138:139]
	s_waitcnt vmcnt(13)
	v_lshlrev_b32_e32 v126, 16, v180
	v_and_b32_e32 v127, 0xffff0000, v180
	v_lshlrev_b32_e32 v116, 16, v181
	v_and_b32_e32 v117, 0xffff0000, v181
	s_waitcnt vmcnt(12)
	v_lshlrev_b32_e32 v160, 16, v184
	v_and_b32_e32 v161, 0xffff0000, v184
	v_lshlrev_b32_e32 v120, 16, v185
	v_and_b32_e32 v121, 0xffff0000, v185
	v_lshlrev_b32_e32 v128, 16, v182
	v_and_b32_e32 v129, 0xffff0000, v182
	v_lshlrev_b32_e32 v118, 16, v183
	v_and_b32_e32 v119, 0xffff0000, v183
	v_lshlrev_b32_e32 v162, 16, v186
	v_and_b32_e32 v163, 0xffff0000, v186
	v_lshlrev_b32_e32 v122, 16, v187
	v_and_b32_e32 v123, 0xffff0000, v187
	v_add_u32_e32 v178, 0xb0, v148
	v_ashrrev_i32_e32 v179, 31, v178
	v_lshlrev_b64 v[178:179], 12, v[178:179]
	v_lshl_add_u64 v[178:179], s[36:37], 0, v[178:179]
	v_lshl_add_u64 v[178:179], v[178:179], 0, v[138:139]
	global_load_dwordx4 v[180:183], v[178:179], off
	global_load_dwordx4 v[184:187], v[178:179], off offset:256
	v_pk_add_f32 v[112:113], v[112:113], v[116:117]
	v_pk_add_f32 v[110:111], v[110:111], v[126:127]
	v_pk_add_f32 v[104:105], v[104:105], v[120:121]
	v_pk_add_f32 v[102:103], v[102:103], v[160:161]
	v_pk_add_f32 v[108:109], v[108:109], v[118:119]
	v_pk_add_f32 v[106:107], v[106:107], v[128:129]
	v_pk_add_f32 v[116:117], v[100:101], v[122:123]
	v_pk_add_f32 v[118:119], v[98:99], v[162:163]
	v_mul_f32_e32 v100, v111, v111
	v_mul_f32_e32 v101, v113, v113
	v_mul_f32_e32 v120, v103, v103
	v_mul_f32_e32 v121, v105, v105
	v_cvt_pk_bf16_f32 v98, v110, v111
	v_mul_f32_e32 v111, v107, v107
	v_mul_f32_e32 v122, v119, v119
	v_fmac_f32_e32 v100, v110, v110
	v_fmac_f32_e32 v101, v112, v112
	v_fmac_f32_e32 v120, v102, v102
	v_fmac_f32_e32 v121, v104, v104
	v_cvt_pk_bf16_f32 v99, v112, v113
	v_mul_f32_e32 v113, v109, v109
	v_mul_f32_e32 v123, v117, v117
	v_fmac_f32_e32 v111, v106, v106
	v_fmac_f32_e32 v122, v118, v118
	v_add_f32_e32 v100, v100, v101
	v_add_f32_e32 v101, v120, v121
	v_fmac_f32_e32 v113, v108, v108
	v_fmac_f32_e32 v123, v116, v116
	v_add_f32_e32 v100, v111, v100
	v_add_f32_e32 v101, v122, v101
	v_add_f32_e32 v100, v113, v100
	v_add_f32_e32 v101, v123, v101
	v_add_f32_e32 v110, v100, v101
	ds_bpermute_b32 v111, v158, v110
	v_cvt_pk_bf16_f32 v100, v106, v107
	v_cvt_pk_bf16_f32 v101, v108, v109
	global_store_dwordx4 v[124:125], v[98:101], off
	s_waitcnt lgkmcnt(0)
	s_nop 0
	v_add_f32_e32 v98, v110, v111
	ds_bpermute_b32 v99, v157, v98
	v_cvt_pk_bf16_f32 v100, v102, v103
	v_cvt_pk_bf16_f32 v101, v104, v105
	v_cvt_pk_bf16_f32 v102, v118, v119
	v_cvt_pk_bf16_f32 v103, v116, v117
	global_store_dwordx4 v[124:125], v[100:103], off offset:256
	s_and_saveexec_b64 s[24:25], s[2:3]
	s_cbranch_execz .LBB0_1611
	v_lshl_add_u64 v[100:101], v[114:115], 2, s[6:7]
	s_waitcnt lgkmcnt(0)
	v_add_f32_e32 v98, v98, v99
	global_atomic_add_f32 v[100:101], v98, off
.LBB0_1611:
	s_or_b64 exec, exec, s[24:25]
	v_or_b32_e32 v98, 32, v148
	s_waitcnt lgkmcnt(0)
	v_ashrrev_i32_e32 v99, 31, v98
	v_lshlrev_b64 v[100:101], 12, v[98:99]
	v_lshl_add_u64 v[100:101], s[36:37], 0, v[100:101]
	v_lshl_add_u64 v[108:109], v[100:101], 0, v[138:139]
	s_waitcnt vmcnt(15)
	v_lshlrev_b32_e32 v110, 16, v192
	v_and_b32_e32 v111, 0xffff0000, v192
	v_lshlrev_b32_e32 v100, 16, v193
	v_and_b32_e32 v101, 0xffff0000, v193
	s_waitcnt vmcnt(14)
	v_lshlrev_b32_e32 v114, 16, v196
	v_and_b32_e32 v115, 0xffff0000, v196
	v_lshlrev_b32_e32 v104, 16, v197
	v_and_b32_e32 v105, 0xffff0000, v197
	v_lshlrev_b32_e32 v112, 16, v194
	v_and_b32_e32 v113, 0xffff0000, v194
	v_lshlrev_b32_e32 v102, 16, v195
	v_and_b32_e32 v103, 0xffff0000, v195
	v_lshlrev_b32_e32 v116, 16, v198
	v_and_b32_e32 v117, 0xffff0000, v198
	v_lshlrev_b32_e32 v106, 16, v199
	v_and_b32_e32 v107, 0xffff0000, v199
	v_pk_add_f32 v[96:97], v[96:97], v[100:101]
	v_pk_add_f32 v[94:95], v[94:95], v[110:111]
	v_pk_add_f32 v[88:89], v[88:89], v[104:105]
	v_pk_add_f32 v[86:87], v[86:87], v[114:115]
	v_pk_add_f32 v[92:93], v[92:93], v[102:103]
	v_pk_add_f32 v[90:91], v[90:91], v[112:113]
	v_pk_add_f32 v[100:101], v[84:85], v[106:107]
	v_pk_add_f32 v[102:103], v[82:83], v[116:117]
	v_mul_f32_e32 v84, v95, v95
	v_mul_f32_e32 v85, v97, v97
	v_mul_f32_e32 v104, v87, v87
	v_mul_f32_e32 v105, v89, v89
	v_cvt_pk_bf16_f32 v82, v94, v95
	v_mul_f32_e32 v95, v91, v91
	v_mul_f32_e32 v106, v103, v103
	v_fmac_f32_e32 v84, v94, v94
	v_fmac_f32_e32 v85, v96, v96
	v_fmac_f32_e32 v104, v86, v86
	v_fmac_f32_e32 v105, v88, v88
	v_cvt_pk_bf16_f32 v83, v96, v97
	v_mul_f32_e32 v97, v93, v93
	v_mul_f32_e32 v107, v101, v101
	v_fmac_f32_e32 v95, v90, v90
	v_fmac_f32_e32 v106, v102, v102
	v_add_f32_e32 v84, v84, v85
	v_add_f32_e32 v85, v104, v105
	v_fmac_f32_e32 v97, v92, v92
	v_fmac_f32_e32 v107, v100, v100
	v_add_f32_e32 v84, v95, v84
	v_add_f32_e32 v85, v106, v85
	v_add_f32_e32 v84, v97, v84
	v_add_f32_e32 v85, v107, v85
	v_add_f32_e32 v94, v84, v85
	ds_bpermute_b32 v95, v158, v94
	v_cvt_pk_bf16_f32 v84, v90, v91
	v_cvt_pk_bf16_f32 v85, v92, v93
	global_store_dwordx4 v[108:109], v[82:85], off
	s_waitcnt lgkmcnt(0)
	s_nop 0
	v_add_f32_e32 v82, v94, v95
	ds_bpermute_b32 v83, v157, v82
	v_cvt_pk_bf16_f32 v84, v86, v87
	v_cvt_pk_bf16_f32 v85, v88, v89
	v_cvt_pk_bf16_f32 v86, v102, v103
	v_cvt_pk_bf16_f32 v87, v100, v101
	global_store_dwordx4 v[108:109], v[84:87], off offset:256
	s_and_saveexec_b64 s[24:25], s[2:3]
	s_cbranch_execz .LBB0_1613
	v_lshl_add_u64 v[84:85], v[98:99], 2, s[6:7]
	s_waitcnt lgkmcnt(0)
	v_add_f32_e32 v82, v82, v83
	global_atomic_add_f32 v[84:85], v82, off
; __device__ __forceinline__ unsigned cvtpk(float lo, float hi) { f32x2_t v = {lo, hi}; bf16x2_t b = __builtin_convertvector(v, bf16x2_t); return __builtin_bit_cast(unsigned, b); }
; __device__ __forceinline__ float bflo(unsigned w) { return __uint_as_float(w << 16); }
; __device__ __forceinline__ float bfhi(unsigned w) { return __uint_as_float(w & 0xffff0000u); }
;     __device__ __forceinline__ void operator()(const f32x4 (&acc)[2][2][4][2], const Unit& u, int wr, int wc, int fr, int fq) const {
;     ...
;                 const int row = row0 + ai * 128 + m * 16; float s = 0.f;
; #pragma unroll
;                 for (int bj = 0; bj < 2; ++bj) {
;                     const size_t off = (size_t)row * D + col0 + bj * 128;
;                     f32x4 b0, b1;
;                     if (BASE_F32) { b0 = __builtin_nontemporal_load((const f32x4*)(base + off)); b1 = __builtin_nontemporal_load((const f32x4*)(base + off + 4)); }
;                     else { const u32x4 w = *(const u32x4*)(xb + off); b0 = (f32x4){bflo(w.x), bfhi(w.x), bflo(w.y), bfhi(w.y)}; b1 = (f32x4){bflo(w.z), bfhi(w.z), bflo(w.w), bfhi(w.w)}; }
;                     const f32x4 h0 = b0 + acc[ai][bj][m][0] * scale, h1 = b1 + acc[ai][bj][m][1] * scale;
;                     if (OUT_F32) { *(f32x4*)(out + off) = h0; *(f32x4*)(out + off + 4) = h1; }
;                     else { u32x4 w; w.x = cvtpk(h0[0], h0[1]); w.y = cvtpk(h0[2], h0[3]); w.z = cvtpk(h1[0], h1[1]); w.w = cvtpk(h1[2], h1[3]); st16(xb + off, w); }
;                     s += (h0[0] * h0[0] + h0[1] * h0[1]) + (h0[2] * h0[2] + h0[3] * h0[3]) + (h1[0] * h1[0] + h1[1] * h1[1]) + (h1[2] * h1[2] + h1[3] * h1[3]);
;                 }
;                 s += __shfl_xor(s, 16); s += __shfl_xor(s, 32);
;                 if (fq == 0) __hip_atomic_fetch_add(ssq_out + row, s, __ATOMIC_RELAXED, __HIP_MEMORY_SCOPE_AGENT);
.LBB0_1613:
	s_or_b64 exec, exec, s[24:25]
	v_or_b32_e32 v82, 48, v148
	s_waitcnt lgkmcnt(0)
	v_ashrrev_i32_e32 v83, 31, v82
	v_lshlrev_b64 v[84:85], 12, v[82:83]
	v_lshl_add_u64 v[84:85], s[36:37], 0, v[84:85]
	v_lshl_add_u64 v[92:93], v[84:85], 0, v[138:139]
	s_waitcnt vmcnt(15)
	v_lshlrev_b32_e32 v94, 16, v200
	v_and_b32_e32 v95, 0xffff0000, v200
	v_lshlrev_b32_e32 v84, 16, v201
	v_and_b32_e32 v85, 0xffff0000, v201
	s_waitcnt vmcnt(14)
	v_lshlrev_b32_e32 v98, 16, v204
	v_and_b32_e32 v99, 0xffff0000, v204
	v_lshlrev_b32_e32 v88, 16, v205
	v_and_b32_e32 v89, 0xffff0000, v205
	v_lshlrev_b32_e32 v96, 16, v202
	v_and_b32_e32 v97, 0xffff0000, v202
	v_lshlrev_b32_e32 v86, 16, v203
	v_and_b32_e32 v87, 0xffff0000, v203
	v_lshlrev_b32_e32 v100, 16, v206
	v_and_b32_e32 v101, 0xffff0000, v206
	v_lshlrev_b32_e32 v90, 16, v207
	v_and_b32_e32 v91, 0xffff0000, v207
	v_pk_add_f32 v[80:81], v[80:81], v[84:85]
	v_pk_add_f32 v[78:79], v[78:79], v[94:95]
	v_pk_add_f32 v[72:73], v[72:73], v[88:89]
	v_pk_add_f32 v[70:71], v[70:71], v[98:99]
	v_pk_add_f32 v[76:77], v[76:77], v[86:87]
	v_pk_add_f32 v[74:75], v[74:75], v[96:97]
	v_pk_add_f32 v[84:85], v[68:69], v[90:91]
	v_pk_add_f32 v[86:87], v[66:67], v[100:101]
	v_mul_f32_e32 v68, v79, v79
	v_mul_f32_e32 v69, v81, v81
	v_mul_f32_e32 v88, v71, v71
	v_mul_f32_e32 v89, v73, v73
	v_cvt_pk_bf16_f32 v66, v78, v79
	v_mul_f32_e32 v79, v75, v75
	v_mul_f32_e32 v90, v87, v87
	v_fmac_f32_e32 v68, v78, v78
	v_fmac_f32_e32 v69, v80, v80
	v_fmac_f32_e32 v88, v70, v70
	v_fmac_f32_e32 v89, v72, v72
	v_cvt_pk_bf16_f32 v67, v80, v81
	v_mul_f32_e32 v81, v77, v77
	v_mul_f32_e32 v91, v85, v85
	v_fmac_f32_e32 v79, v74, v74
	v_fmac_f32_e32 v90, v86, v86
	v_add_f32_e32 v68, v68, v69
	v_add_f32_e32 v69, v88, v89
	v_fmac_f32_e32 v81, v76, v76
	v_fmac_f32_e32 v91, v84, v84
	v_add_f32_e32 v68, v79, v68
	v_add_f32_e32 v69, v90, v69
	v_add_f32_e32 v68, v81, v68
	v_add_f32_e32 v69, v91, v69
	v_add_f32_e32 v78, v68, v69
	ds_bpermute_b32 v79, v158, v78
	v_cvt_pk_bf16_f32 v68, v74, v75
	v_cvt_pk_bf16_f32 v69, v76, v77
	global_store_dwordx4 v[92:93], v[66:69], off
	s_waitcnt lgkmcnt(0)
	s_nop 0
	v_add_f32_e32 v66, v78, v79
	ds_bpermute_b32 v67, v157, v66
	v_cvt_pk_bf16_f32 v68, v70, v71
	v_cvt_pk_bf16_f32 v69, v72, v73
	v_cvt_pk_bf16_f32 v70, v86, v87
	v_cvt_pk_bf16_f32 v71, v84, v85
	global_store_dwordx4 v[92:93], v[68:71], off offset:256
	s_and_saveexec_b64 s[24:25], s[2:3]
	s_cbranch_execz .LBB0_1615
	v_lshl_add_u64 v[68:69], v[82:83], 2, s[6:7]
	s_waitcnt lgkmcnt(0)
	v_add_f32_e32 v66, v66, v67
	global_atomic_add_f32 v[68:69], v66, off
.LBB0_1615:
	s_or_b64 exec, exec, s[24:25]
	v_add_u32_e32 v66, 0x80, v148
	s_waitcnt lgkmcnt(0)
	v_ashrrev_i32_e32 v67, 31, v66
	v_lshlrev_b64 v[68:69], 12, v[66:67]
	v_lshl_add_u64 v[68:69], s[36:37], 0, v[68:69]
	v_lshl_add_u64 v[76:77], v[68:69], 0, v[138:139]
	s_waitcnt vmcnt(15)
	v_lshlrev_b32_e32 v78, 16, v208
	v_and_b32_e32 v79, 0xffff0000, v208
	v_lshlrev_b32_e32 v68, 16, v209
	v_and_b32_e32 v69, 0xffff0000, v209
	s_waitcnt vmcnt(14)
	v_lshlrev_b32_e32 v82, 16, v212
	v_and_b32_e32 v83, 0xffff0000, v212
	v_lshlrev_b32_e32 v72, 16, v213
	v_and_b32_e32 v73, 0xffff0000, v213
	v_lshlrev_b32_e32 v80, 16, v210
	v_and_b32_e32 v81, 0xffff0000, v210
	v_lshlrev_b32_e32 v70, 16, v211
	v_and_b32_e32 v71, 0xffff0000, v211
	v_lshlrev_b32_e32 v84, 16, v214
	v_and_b32_e32 v85, 0xffff0000, v214
	v_lshlrev_b32_e32 v74, 16, v215
	v_and_b32_e32 v75, 0xffff0000, v215
	v_pk_add_f32 v[64:65], v[64:65], v[68:69]
	v_pk_add_f32 v[62:63], v[62:63], v[78:79]
	v_pk_add_f32 v[56:57], v[56:57], v[72:73]
	v_pk_add_f32 v[54:55], v[54:55], v[82:83]
	v_pk_add_f32 v[60:61], v[60:61], v[70:71]
	v_pk_add_f32 v[58:59], v[58:59], v[80:81]
	v_pk_add_f32 v[68:69], v[52:53], v[74:75]
	v_pk_add_f32 v[70:71], v[50:51], v[84:85]
	v_mul_f32_e32 v52, v63, v63
	v_mul_f32_e32 v53, v65, v65
	v_mul_f32_e32 v72, v55, v55
	v_mul_f32_e32 v73, v57, v57
	v_cvt_pk_bf16_f32 v50, v62, v63
	v_mul_f32_e32 v63, v59, v59
	v_mul_f32_e32 v74, v71, v71
	v_fmac_f32_e32 v52, v62, v62
	v_fmac_f32_e32 v53, v64, v64
	v_fmac_f32_e32 v72, v54, v54
	v_fmac_f32_e32 v73, v56, v56
	v_cvt_pk_bf16_f32 v51, v64, v65
	v_mul_f32_e32 v65, v61, v61
	v_mul_f32_e32 v75, v69, v69
	v_fmac_f32_e32 v63, v58, v58
	v_fmac_f32_e32 v74, v70, v70
	v_add_f32_e32 v52, v52, v53
	v_add_f32_e32 v53, v72, v73
	v_fmac_f32_e32 v65, v60, v60
	v_fmac_f32_e32 v75, v68, v68
	v_add_f32_e32 v52, v63, v52
	v_add_f32_e32 v53, v74, v53
	v_add_f32_e32 v52, v65, v52
	v_add_f32_e32 v53, v75, v53
	v_add_f32_e32 v62, v52, v53
	ds_bpermute_b32 v63, v158, v62
	v_cvt_pk_bf16_f32 v52, v58, v59
	v_cvt_pk_bf16_f32 v53, v60, v61
	global_store_dwordx4 v[76:77], v[50:53], off
	s_waitcnt lgkmcnt(0)
	s_nop 0
	v_add_f32_e32 v50, v62, v63
	ds_bpermute_b32 v51, v157, v50
	v_cvt_pk_bf16_f32 v52, v54, v55
	v_cvt_pk_bf16_f32 v53, v56, v57
	v_cvt_pk_bf16_f32 v54, v70, v71
	v_cvt_pk_bf16_f32 v55, v68, v69
	global_store_dwordx4 v[76:77], v[52:55], off offset:256
	s_and_saveexec_b64 s[24:25], s[2:3]
	s_cbranch_execz .LBB0_1617
	v_lshl_add_u64 v[52:53], v[66:67], 2, s[6:7]
	s_waitcnt lgkmcnt(0)
	v_add_f32_e32 v50, v50, v51
	global_atomic_add_f32 v[52:53], v50, off
; __device__ __forceinline__ unsigned cvtpk(float lo, float hi) { f32x2_t v = {lo, hi}; bf16x2_t b = __builtin_convertvector(v, bf16x2_t); return __builtin_bit_cast(unsigned, b); }
; __device__ __forceinline__ float bflo(unsigned w) { return __uint_as_float(w << 16); }
; __device__ __forceinline__ float bfhi(unsigned w) { return __uint_as_float(w & 0xffff0000u); }
;     __device__ __forceinline__ void operator()(const f32x4 (&acc)[2][2][4][2], const Unit& u, int wr, int wc, int fr, int fq) const {
;     ...
;                 const int row = row0 + ai * 128 + m * 16; float s = 0.f;
; #pragma unroll
;                 for (int bj = 0; bj < 2; ++bj) {
;                     const size_t off = (size_t)row * D + col0 + bj * 128;
;                     f32x4 b0, b1;
;                     if (BASE_F32) { b0 = __builtin_nontemporal_load((const f32x4*)(base + off)); b1 = __builtin_nontemporal_load((const f32x4*)(base + off + 4)); }
;                     else { const u32x4 w = *(const u32x4*)(xb + off); b0 = (f32x4){bflo(w.x), bfhi(w.x), bflo(w.y), bfhi(w.y)}; b1 = (f32x4){bflo(w.z), bfhi(w.z), bflo(w.w), bfhi(w.w)}; }
;                     const f32x4 h0 = b0 + acc[ai][bj][m][0] * scale, h1 = b1 + acc[ai][bj][m][1] * scale;
;                     if (OUT_F32) { *(f32x4*)(out + off) = h0; *(f32x4*)(out + off + 4) = h1; }
;                     else { u32x4 w; w.x = cvtpk(h0[0], h0[1]); w.y = cvtpk(h0[2], h0[3]); w.z = cvtpk(h1[0], h1[1]); w.w = cvtpk(h1[2], h1[3]); st16(xb + off, w); }
;                     s += (h0[0] * h0[0] + h0[1] * h0[1]) + (h0[2] * h0[2] + h0[3] * h0[3]) + (h1[0] * h1[0] + h1[1] * h1[1]) + (h1[2] * h1[2] + h1[3] * h1[3]);
;                 }
;                 s += __shfl_xor(s, 16); s += __shfl_xor(s, 32);
;                 if (fq == 0) __hip_atomic_fetch_add(ssq_out + row, s, __ATOMIC_RELAXED, __HIP_MEMORY_SCOPE_AGENT);
.LBB0_1617:
	s_or_b64 exec, exec, s[24:25]
	v_add_u32_e32 v50, 0x90, v148
	s_waitcnt lgkmcnt(0)
	v_ashrrev_i32_e32 v51, 31, v50
	v_lshlrev_b64 v[52:53], 12, v[50:51]
	v_lshl_add_u64 v[52:53], s[36:37], 0, v[52:53]
	v_lshl_add_u64 v[60:61], v[52:53], 0, v[138:139]
	s_waitcnt vmcnt(15)
	v_lshlrev_b32_e32 v62, 16, v216
	v_and_b32_e32 v63, 0xffff0000, v216
	v_lshlrev_b32_e32 v52, 16, v217
	v_and_b32_e32 v53, 0xffff0000, v217
	s_waitcnt vmcnt(14)
	v_lshlrev_b32_e32 v66, 16, v220
	v_and_b32_e32 v67, 0xffff0000, v220
	v_lshlrev_b32_e32 v56, 16, v221
	v_and_b32_e32 v57, 0xffff0000, v221
	v_lshlrev_b32_e32 v64, 16, v218
	v_and_b32_e32 v65, 0xffff0000, v218
	v_lshlrev_b32_e32 v54, 16, v219
	v_and_b32_e32 v55, 0xffff0000, v219
	v_lshlrev_b32_e32 v68, 16, v222
	v_and_b32_e32 v69, 0xffff0000, v222
	v_lshlrev_b32_e32 v58, 16, v223
	v_and_b32_e32 v59, 0xffff0000, v223
	v_pk_add_f32 v[48:49], v[48:49], v[52:53]
	v_pk_add_f32 v[46:47], v[46:47], v[62:63]
	v_pk_add_f32 v[40:41], v[40:41], v[56:57]
	v_pk_add_f32 v[38:39], v[38:39], v[66:67]
	v_pk_add_f32 v[44:45], v[44:45], v[54:55]
	v_pk_add_f32 v[42:43], v[42:43], v[64:65]
	v_pk_add_f32 v[52:53], v[36:37], v[58:59]
	v_pk_add_f32 v[54:55], v[34:35], v[68:69]
	v_mul_f32_e32 v36, v47, v47
	v_mul_f32_e32 v37, v49, v49
	v_mul_f32_e32 v56, v39, v39
	v_mul_f32_e32 v57, v41, v41
	v_cvt_pk_bf16_f32 v34, v46, v47
	v_mul_f32_e32 v47, v43, v43
	v_mul_f32_e32 v58, v55, v55
	v_fmac_f32_e32 v36, v46, v46
	v_fmac_f32_e32 v37, v48, v48
	v_fmac_f32_e32 v56, v38, v38
	v_fmac_f32_e32 v57, v40, v40
	v_cvt_pk_bf16_f32 v35, v48, v49
	v_mul_f32_e32 v49, v45, v45
	v_mul_f32_e32 v59, v53, v53
	v_fmac_f32_e32 v47, v42, v42
	v_fmac_f32_e32 v58, v54, v54
	v_add_f32_e32 v36, v36, v37
	v_add_f32_e32 v37, v56, v57
	v_fmac_f32_e32 v49, v44, v44
	v_fmac_f32_e32 v59, v52, v52
	v_add_f32_e32 v36, v47, v36
	v_add_f32_e32 v37, v58, v37
	v_add_f32_e32 v36, v49, v36
	v_add_f32_e32 v37, v59, v37
	v_add_f32_e32 v46, v36, v37
	ds_bpermute_b32 v47, v158, v46
	v_cvt_pk_bf16_f32 v36, v42, v43
	v_cvt_pk_bf16_f32 v37, v44, v45
	global_store_dwordx4 v[60:61], v[34:37], off
	s_waitcnt lgkmcnt(0)
	s_nop 0
	v_add_f32_e32 v34, v46, v47
	ds_bpermute_b32 v35, v157, v34
	v_cvt_pk_bf16_f32 v36, v38, v39
	v_cvt_pk_bf16_f32 v37, v40, v41
	v_cvt_pk_bf16_f32 v38, v54, v55
	v_cvt_pk_bf16_f32 v39, v52, v53
	global_store_dwordx4 v[60:61], v[36:39], off offset:256
	s_and_saveexec_b64 s[24:25], s[2:3]
	s_cbranch_execz .LBB0_1619
	v_lshl_add_u64 v[36:37], v[50:51], 2, s[6:7]
	s_waitcnt lgkmcnt(0)
	v_add_f32_e32 v34, v34, v35
	global_atomic_add_f32 v[36:37], v34, off
; __device__ __forceinline__ unsigned cvtpk(float lo, float hi) { f32x2_t v = {lo, hi}; bf16x2_t b = __builtin_convertvector(v, bf16x2_t); return __builtin_bit_cast(unsigned, b); }
; __device__ __forceinline__ float bflo(unsigned w) { return __uint_as_float(w << 16); }
; __device__ __forceinline__ float bfhi(unsigned w) { return __uint_as_float(w & 0xffff0000u); }
;     __device__ __forceinline__ void operator()(const f32x4 (&acc)[2][2][4][2], const Unit& u, int wr, int wc, int fr, int fq) const {
;     ...
;                 const int row = row0 + ai * 128 + m * 16; float s = 0.f;
; #pragma unroll
;                 for (int bj = 0; bj < 2; ++bj) {
;                     const size_t off = (size_t)row * D + col0 + bj * 128;
;                     f32x4 b0, b1;
;                     if (BASE_F32) { b0 = __builtin_nontemporal_load((const f32x4*)(base + off)); b1 = __builtin_nontemporal_load((const f32x4*)(base + off + 4)); }
;                     else { const u32x4 w = *(const u32x4*)(xb + off); b0 = (f32x4){bflo(w.x), bfhi(w.x), bflo(w.y), bfhi(w.y)}; b1 = (f32x4){bflo(w.z), bfhi(w.z), bflo(w.w), bfhi(w.w)}; }
;                     const f32x4 h0 = b0 + acc[ai][bj][m][0] * scale, h1 = b1 + acc[ai][bj][m][1] * scale;
;                     if (OUT_F32) { *(f32x4*)(out + off) = h0; *(f32x4*)(out + off + 4) = h1; }
;                     else { u32x4 w; w.x = cvtpk(h0[0], h0[1]); w.y = cvtpk(h0[2], h0[3]); w.z = cvtpk(h1[0], h1[1]); w.w = cvtpk(h1[2], h1[3]); st16(xb + off, w); }
;                     s += (h0[0] * h0[0] + h0[1] * h0[1]) + (h0[2] * h0[2] + h0[3] * h0[3]) + (h1[0] * h1[0] + h1[1] * h1[1]) + (h1[2] * h1[2] + h1[3] * h1[3]);
;                 }
;                 s += __shfl_xor(s, 16); s += __shfl_xor(s, 32);
;                 if (fq == 0) __hip_atomic_fetch_add(ssq_out + row, s, __ATOMIC_RELAXED, __HIP_MEMORY_SCOPE_AGENT);
.LBB0_1619:
	s_or_b64 exec, exec, s[24:25]
	v_add_u32_e32 v34, 0xa0, v148
	s_waitcnt lgkmcnt(0)
	v_ashrrev_i32_e32 v35, 31, v34
	v_lshlrev_b64 v[36:37], 12, v[34:35]
	v_lshl_add_u64 v[36:37], s[36:37], 0, v[36:37]
	v_lshl_add_u64 v[44:45], v[36:37], 0, v[138:139]
	s_waitcnt vmcnt(15)
	v_lshlrev_b32_e32 v46, 16, v224
	v_and_b32_e32 v47, 0xffff0000, v224
	v_lshlrev_b32_e32 v36, 16, v225
	v_and_b32_e32 v37, 0xffff0000, v225
	s_waitcnt vmcnt(14)
	v_lshlrev_b32_e32 v50, 16, v228
	v_and_b32_e32 v51, 0xffff0000, v228
	v_lshlrev_b32_e32 v40, 16, v229
	v_and_b32_e32 v41, 0xffff0000, v229
	v_lshlrev_b32_e32 v48, 16, v226
	v_and_b32_e32 v49, 0xffff0000, v226
	v_lshlrev_b32_e32 v38, 16, v227
	v_and_b32_e32 v39, 0xffff0000, v227
	v_lshlrev_b32_e32 v52, 16, v230
	v_and_b32_e32 v53, 0xffff0000, v230
	v_lshlrev_b32_e32 v42, 16, v231
	v_and_b32_e32 v43, 0xffff0000, v231
	v_pk_add_f32 v[32:33], v[32:33], v[36:37]
	v_pk_add_f32 v[30:31], v[30:31], v[46:47]
	v_pk_add_f32 v[24:25], v[24:25], v[40:41]
	v_pk_add_f32 v[22:23], v[22:23], v[50:51]
	v_pk_add_f32 v[28:29], v[28:29], v[38:39]
	v_pk_add_f32 v[26:27], v[26:27], v[48:49]
	v_pk_add_f32 v[36:37], v[20:21], v[42:43]
	v_pk_add_f32 v[38:39], v[18:19], v[52:53]
	v_mul_f32_e32 v20, v31, v31
	v_mul_f32_e32 v21, v33, v33
	v_mul_f32_e32 v40, v23, v23
	v_mul_f32_e32 v41, v25, v25
	v_cvt_pk_bf16_f32 v18, v30, v31
	v_mul_f32_e32 v31, v27, v27
	v_mul_f32_e32 v42, v39, v39
	v_fmac_f32_e32 v20, v30, v30
	v_fmac_f32_e32 v21, v32, v32
	v_fmac_f32_e32 v40, v22, v22
	v_fmac_f32_e32 v41, v24, v24
	v_cvt_pk_bf16_f32 v19, v32, v33
	v_mul_f32_e32 v33, v29, v29
	v_mul_f32_e32 v43, v37, v37
	v_fmac_f32_e32 v31, v26, v26
	v_fmac_f32_e32 v42, v38, v38
	v_add_f32_e32 v20, v20, v21
	v_add_f32_e32 v21, v40, v41
	v_fmac_f32_e32 v33, v28, v28
	v_fmac_f32_e32 v43, v36, v36
	v_add_f32_e32 v20, v31, v20
	v_add_f32_e32 v21, v42, v21
	v_add_f32_e32 v20, v33, v20
	v_add_f32_e32 v21, v43, v21
	v_add_f32_e32 v30, v20, v21
	ds_bpermute_b32 v31, v158, v30
	v_cvt_pk_bf16_f32 v20, v26, v27
	v_cvt_pk_bf16_f32 v21, v28, v29
	global_store_dwordx4 v[44:45], v[18:21], off
	s_waitcnt lgkmcnt(0)
	s_nop 0
	v_add_f32_e32 v18, v30, v31
	ds_bpermute_b32 v19, v157, v18
	v_cvt_pk_bf16_f32 v20, v22, v23
	v_cvt_pk_bf16_f32 v21, v24, v25
	v_cvt_pk_bf16_f32 v22, v38, v39
	v_cvt_pk_bf16_f32 v23, v36, v37
	global_store_dwordx4 v[44:45], v[20:23], off offset:256
	s_and_saveexec_b64 s[24:25], s[2:3]
	s_cbranch_execz .LBB0_1621
	v_lshl_add_u64 v[20:21], v[34:35], 2, s[6:7]
	s_waitcnt lgkmcnt(0)
	v_add_f32_e32 v18, v18, v19
	global_atomic_add_f32 v[20:21], v18, off
.LBB0_1621:
	s_or_b64 exec, exec, s[24:25]
	v_add_u32_e32 v18, 0xb0, v148
	s_waitcnt lgkmcnt(0)
	v_ashrrev_i32_e32 v19, 31, v18
	v_lshlrev_b64 v[20:21], 12, v[18:19]
	v_lshl_add_u64 v[20:21], s[36:37], 0, v[20:21]
	v_lshl_add_u64 v[28:29], v[20:21], 0, v[138:139]
	s_waitcnt vmcnt(13)
	v_lshlrev_b32_e32 v30, 16, v180
	v_and_b32_e32 v31, 0xffff0000, v180
	v_lshlrev_b32_e32 v20, 16, v181
	v_and_b32_e32 v21, 0xffff0000, v181
	s_waitcnt vmcnt(12)
	v_lshlrev_b32_e32 v34, 16, v184
	v_and_b32_e32 v35, 0xffff0000, v184
	v_lshlrev_b32_e32 v24, 16, v185
	v_and_b32_e32 v25, 0xffff0000, v185
	v_lshlrev_b32_e32 v32, 16, v182
	v_and_b32_e32 v33, 0xffff0000, v182
	v_lshlrev_b32_e32 v22, 16, v183
	v_and_b32_e32 v23, 0xffff0000, v183
	v_lshlrev_b32_e32 v36, 16, v186
	v_and_b32_e32 v37, 0xffff0000, v186
	v_lshlrev_b32_e32 v26, 16, v187
	v_and_b32_e32 v27, 0xffff0000, v187
	v_pk_add_f32 v[16:17], v[16:17], v[20:21]
	v_pk_add_f32 v[14:15], v[14:15], v[30:31]
	v_pk_add_f32 v[8:9], v[8:9], v[24:25]
	v_pk_add_f32 v[6:7], v[6:7], v[34:35]
	v_pk_add_f32 v[12:13], v[12:13], v[22:23]
	v_pk_add_f32 v[10:11], v[10:11], v[32:33]
	v_pk_add_f32 v[20:21], v[4:5], v[26:27]
	v_pk_add_f32 v[22:23], v[2:3], v[36:37]
	v_mul_f32_e32 v4, v15, v15
	v_mul_f32_e32 v5, v17, v17
	v_mul_f32_e32 v24, v7, v7
	v_mul_f32_e32 v25, v9, v9
	v_cvt_pk_bf16_f32 v2, v14, v15
	v_mul_f32_e32 v15, v11, v11
	v_mul_f32_e32 v26, v23, v23
	v_fmac_f32_e32 v4, v14, v14
	v_fmac_f32_e32 v5, v16, v16
	v_fmac_f32_e32 v24, v6, v6
	v_fmac_f32_e32 v25, v8, v8
	v_cvt_pk_bf16_f32 v3, v16, v17
	v_mul_f32_e32 v17, v13, v13
	v_mul_f32_e32 v27, v21, v21
	v_fmac_f32_e32 v15, v10, v10
	v_fmac_f32_e32 v26, v22, v22
	v_add_f32_e32 v4, v4, v5
	v_add_f32_e32 v5, v24, v25
	v_fmac_f32_e32 v17, v12, v12
	v_fmac_f32_e32 v27, v20, v20
	v_add_f32_e32 v4, v15, v4
	v_add_f32_e32 v5, v26, v5
	v_add_f32_e32 v4, v17, v4
	v_add_f32_e32 v5, v27, v5
	v_add_f32_e32 v14, v4, v5
	ds_bpermute_b32 v15, v158, v14
	v_cvt_pk_bf16_f32 v4, v10, v11
	v_cvt_pk_bf16_f32 v5, v12, v13
	global_store_dwordx4 v[28:29], v[2:5], off
	s_waitcnt lgkmcnt(0)
	s_nop 0
	v_add_f32_e32 v2, v14, v15
	ds_bpermute_b32 v3, v157, v2
	v_cvt_pk_bf16_f32 v4, v6, v7
	v_cvt_pk_bf16_f32 v5, v8, v9
	v_cvt_pk_bf16_f32 v6, v22, v23
	v_cvt_pk_bf16_f32 v7, v20, v21
	global_store_dwordx4 v[28:29], v[4:7], off offset:256
	s_and_saveexec_b64 s[24:25], s[2:3]
	s_cbranch_execz .LBB0_1623
	v_lshl_add_u64 v[4:5], v[18:19], 2, s[6:7]
	s_waitcnt lgkmcnt(0)
	v_add_f32_e32 v2, v2, v3
	global_atomic_add_f32 v[4:5], v2, off
